# LN rows XCD-aligned with out-GEMM tiles; HY(h) stored pair-interleaved so each in-GEMM A-tile LDS-DMA instruction reads full 128B lines
# speedup vs baseline: 1.0919x; 1.0216x over previous
; DI int otid() { int t = threadIdx.x; asm volatile("" : "+v"(t)); return t; }
; DI void phase_ln(const Ctx& c, int l_post, int l_next) {
;   const int tid = otid(), lane = tid & 63;
;   const int wv = (blockIdx.x * NT + tid) >> 6, nw = (gridDim.x * NT) >> 6;
;   for (int row = wv; row < MT; row += 2 * nw) { ln_row(c, row, l_post, l_next, lane); if (row + nw < MT) ln_row(c, row + nw, l_post, l_next, lane); }
.Lln0_entry:
	v_readlane_b32 s4, v252, 32
	v_lshrrev_b32_e32 v2, 6, v172
	s_nop 0
	v_readfirstlane_b32 s5, v2
	s_lshr_b32 s4, s4, 8
	s_and_b32 s13, s4, 7
	s_lshr_b32 s4, s4, 3
	s_lshl_b32 s4, s4, 2
	s_add_i32 s5, s4, s5
	s_lshl_b32 s6, s13, 11
	s_add_i32 s6, s6, s5
	s_lshl_b32 s13, s13, 6
	s_add_i32 s13, s13, s5
	s_addk_i32 s13, 0x4000
	s_cmp_lt_u32 s5, 64
	s_cselect_b32 s13, s13, 0
	s_mov_b32 s12, 0
	v_mbcnt_lo_u32_b32 v2, -1, 0
	v_mbcnt_hi_u32_b32 v2, -1, v2
	v_xor_b32_e32 v5, 16, v2
	v_lshlrev_b32_e32 v5, 2, v5
	v_lshrrev_b32_e32 v14, 3, v2
	v_lshlrev_b32_e32 v14, 7, v14
	v_and_b32_e32 v6, 7, v2
	v_lshl_or_b32 v14, v6, 3, v14
	v_lshlrev_b32_e32 v2, 4, v2
	s_mov_b64 s[30:31], s[44:45]
	s_mov_b64 s[28:29], s[48:49]
	s_mov_b32 s20, 0
	s_cmp_lt_u32 s6, 0x4000
	s_cbranch_scc0 .Lln0_c0
	s_lshl_b32 s2, s6, 12
	s_add_u32 s2, s30, s2
	s_addc_u32 s3, s31, 0
	s_lshr_b32 s8, s6, 13
	s_branch .Lln0_j0

; DI int otid() { int t = threadIdx.x; asm volatile("" : "+v"(t)); return t; }
; DI void phase_ln(const Ctx& c, int l_post, int l_next) {
;   const int tid = otid(), lane = tid & 63;
;   const int wv = (blockIdx.x * NT + tid) >> 6, nw = (gridDim.x * NT) >> 6;
;   for (int row = wv; row < MT; row += 2 * nw) { ln_row(c, row, l_post, l_next, lane); if (row + nw < MT) ln_row(c, row + nw, l_post, l_next, lane); }
.Lln0_loop:
	s_add_u32 s12, s12, 1
	s_cmp_lt_u32 s12, 8
	s_cbranch_scc0 .Lln0_chk9A
	s_add_u32 s7, s6, 0x100
	s_branch .Lln0_preA
.Lln0_chk9A:
	s_cmp_eq_u32 s12, 8
	s_cbranch_scc0 .Lln0_lastA
	s_cmp_eq_u32 s13, 0
	s_cbranch_scc1 .Lln0_lastA
	s_mov_b32 s7, s13
.Lln0_preA:
	s_cmp_lt_u32 s7, 0x4000
	s_cbranch_scc0 .Lln0_c1
	s_lshl_b32 s2, s7, 12
	s_add_u32 s2, s30, s2
	s_addc_u32 s3, s31, 0
	s_lshr_b32 s8, s7, 13
	s_branch .Lln0_j1

; DI bf16 f2bf(float f) { unsigned u = __float_as_uint(f); u += 0x7fffu + ((u >> 16) & 1u); return (bf16)(u >> 16); }
; DI void ln_row(const Ctx& c, int row, int l_post, int l_next, int lane) {
;     ...
;     for (int i = 0; i < 4; ++i) { const float4 t = *(const float4*)(src + i * 256 + lane * 4); v[i * 4] = t.x; v[i * 4 + 1] = t.y; v[i * 4 + 2] = t.z; v[i * 4 + 3] = t.w; }
;     if (do_post) {
;       float s = 0.f;
; #pragma unroll
;       for (int i = 0; i < 16; ++i) s += v[i];
;       const float mean = wave_sum(s) * (1.f / D);
;       float q = 0.f;
; #pragma unroll
;       for (int i = 0; i < 16; ++i) { v[i] -= mean; q += v[i] * v[i]; }
;       const float rstd = rsqrtf(wave_sum(q) * (1.f / D) + LN_EPS);
;       float* dst = c.xrow(row);
; #pragma unroll
;       for (int i = 0; i < 4; ++i) {
;         const int col = i * 256 + lane * 4;
;         const float4 g = *(const float4*)(p.post_g + l_post * D + col), b = *(const float4*)(p.post_b + l_post * D + col);
;         v[i * 4] = v[i * 4] * rstd * g.x + b.x; v[i * 4 + 1] = v[i * 4 + 1] * rstd * g.y + b.y;
;         v[i * 4 + 2] = v[i * 4 + 2] * rstd * g.z + b.z; v[i * 4 + 3] = v[i * 4 + 3] * rstd * g.w + b.w;
;         *(float4*)(dst + col) = make_float4(v[i * 4], v[i * 4 + 1], v[i * 4 + 2], v[i * 4 + 3]);
;       }
;     }
;     if (do_h) {
;       float s = 0.f;
; #pragma unroll
;       for (int i = 0; i < 16; ++i) s += v[i];
;       const float mean = wave_sum(s) * (1.f / D);
;       float q = 0.f;
; #pragma unroll
;       for (int i = 0; i < 16; ++i) { v[i] -= mean; q += v[i] * v[i]; }
;       const float rstd = rsqrtf(wave_sum(q) * (1.f / D) + LN_EPS);
;       const float* md = c.MOD() + (l_next * 3 + mod_row(row)) * 3072;
;       bf16* dst = c.HY() + (size_t)row * D;
; #pragma unroll
;       for (int i = 0; i < 4; ++i) {
;         const int col = i * 256 + lane * 4;
;         const float4 sh = *(const float4*)(md + col), sc = *(const float4*)(md + 1024 + col);
;         const float h0 = v[i * 4] * rstd * (1.f + sc.x) + sh.x, h1 = v[i * 4 + 1] * rstd * (1.f + sc.y) + sh.y;
;         const float h2 = v[i * 4 + 2] * rstd * (1.f + sc.z) + sh.z, h3 = v[i * 4 + 3] * rstd * (1.f + sc.w) + sh.w;
;         uint2 pk; pk.x = (unsigned)f2bf(h0) | ((unsigned)f2bf(h1) << 16); pk.y = (unsigned)f2bf(h2) | ((unsigned)f2bf(h3) << 16);
;         *(uint2*)(dst + col) = pk;
;       }
.Lln0_j1:
	global_load_dwordx4 v[68:71], v2, s[2:3] offset:0
	global_load_dwordx4 v[72:75], v2, s[2:3] offset:1024
	global_load_dwordx4 v[76:79], v2, s[2:3] offset:2048
	global_load_dwordx4 v[80:83], v2, s[2:3] offset:3072
	s_add_u32 s8, s8, s20
	s_mul_i32 s8, s8, 0x3000
	s_add_u32 s10, s88, s8
	s_addc_u32 s11, s89, 0
	s_add_u32 s10, s10, 0x4000
	s_addc_u32 s11, s11, 0
	global_load_dwordx4 v[116:119], v2, s[10:11] offset:0
	global_load_dwordx4 v[120:123], v2, s[10:11] offset:1024
	global_load_dwordx4 v[124:127], v2, s[10:11] offset:2048
	global_load_dwordx4 v[128:131], v2, s[10:11] offset:3072
	s_add_u32 s10, s10, 0x1000
	s_addc_u32 s11, s11, 0
	global_load_dwordx4 v[132:135], v2, s[10:11] offset:0
	global_load_dwordx4 v[136:139], v2, s[10:11] offset:1024
	global_load_dwordx4 v[140:143], v2, s[10:11] offset:2048
	global_load_dwordx4 v[144:147], v2, s[10:11] offset:3072
	s_waitcnt vmcnt(12)
	s_lshr_b32 s26, s6, 1
	s_lshl_b32 s26, s26, 12
	s_and_b32 s2, s6, 1
	s_lshl_b32 s2, s2, 6
	s_or_b32 s26, s26, s2
	s_add_u32 s26, s88, s26
	s_addc_u32 s27, s89, 0
	s_add_u32 s26, s26, 0x1128000
	s_addc_u32 s27, s27, 0
	v_add_f32_e32 v6, v52, v53
	v_add_f32_e32 v6, v6, v54
	v_add_f32_e32 v6, v6, v55
	v_add_f32_e32 v6, v6, v56
	v_add_f32_e32 v6, v6, v57
	v_add_f32_e32 v6, v6, v58
	v_add_f32_e32 v6, v6, v59
	v_add_f32_e32 v6, v6, v60
	v_add_f32_e32 v6, v6, v61
	v_add_f32_e32 v6, v6, v62
	v_add_f32_e32 v6, v6, v63
	v_add_f32_e32 v6, v6, v64
	v_add_f32_e32 v6, v6, v65
	v_add_f32_e32 v6, v6, v66
	v_add_f32_e32 v6, v6, v67
	s_nop 1
	v_add_f32_dpp v6, v6, v6 row_ror:8 row_mask:0xf bank_mask:0xf bound_ctrl:1
	s_nop 1
	v_add_f32_dpp v6, v6, v6 row_ror:4 row_mask:0xf bank_mask:0xf bound_ctrl:1
	s_nop 1
	v_add_f32_dpp v6, v6, v6 row_ror:2 row_mask:0xf bank_mask:0xf bound_ctrl:1
	s_nop 1
	v_add_f32_dpp v6, v6, v6 row_ror:1 row_mask:0xf bank_mask:0xf bound_ctrl:1
	ds_bpermute_b32 v8, v5, v6
	s_waitcnt lgkmcnt(0)
	v_add_f32_e32 v6, v6, v8
	v_mov_b32_e32 v8, v6
	s_nop 1
	v_permlane32_swap_b32_e32 v6, v8
	v_add_f32_e32 v6, v6, v8
	v_mul_f32_e32 v6, 0x3a800000, v6
	v_sub_f32_e32 v52, v52, v6
	v_sub_f32_e32 v53, v53, v6
	v_sub_f32_e32 v54, v54, v6
	v_sub_f32_e32 v55, v55, v6
	v_sub_f32_e32 v56, v56, v6
	v_sub_f32_e32 v57, v57, v6
	v_sub_f32_e32 v58, v58, v6
	v_sub_f32_e32 v59, v59, v6
	v_sub_f32_e32 v60, v60, v6
	v_sub_f32_e32 v61, v61, v6
	v_sub_f32_e32 v62, v62, v6
	v_sub_f32_e32 v63, v63, v6
	v_sub_f32_e32 v64, v64, v6
	v_sub_f32_e32 v65, v65, v6
	v_sub_f32_e32 v66, v66, v6
	v_sub_f32_e32 v67, v67, v6
	v_mul_f32_e32 v7, v52, v52
	v_fmac_f32_e32 v7, v53, v53
	v_fmac_f32_e32 v7, v54, v54
	v_fmac_f32_e32 v7, v55, v55
	v_fmac_f32_e32 v7, v56, v56
	v_fmac_f32_e32 v7, v57, v57
	v_fmac_f32_e32 v7, v58, v58
	v_fmac_f32_e32 v7, v59, v59
	v_fmac_f32_e32 v7, v60, v60
	v_fmac_f32_e32 v7, v61, v61
	v_fmac_f32_e32 v7, v62, v62
	v_fmac_f32_e32 v7, v63, v63
	v_fmac_f32_e32 v7, v64, v64
	v_fmac_f32_e32 v7, v65, v65
	v_fmac_f32_e32 v7, v66, v66
	v_fmac_f32_e32 v7, v67, v67
	s_nop 1
	v_add_f32_dpp v7, v7, v7 row_ror:8 row_mask:0xf bank_mask:0xf bound_ctrl:1
	s_nop 1
	v_add_f32_dpp v7, v7, v7 row_ror:4 row_mask:0xf bank_mask:0xf bound_ctrl:1
	s_nop 1
	v_add_f32_dpp v7, v7, v7 row_ror:2 row_mask:0xf bank_mask:0xf bound_ctrl:1
	s_nop 1
	v_add_f32_dpp v7, v7, v7 row_ror:1 row_mask:0xf bank_mask:0xf bound_ctrl:1
	ds_bpermute_b32 v8, v5, v7
	s_waitcnt lgkmcnt(0)
	v_add_f32_e32 v7, v7, v8
	v_mov_b32_e32 v8, v7
	s_nop 1
	v_permlane32_swap_b32_e32 v7, v8
	v_add_f32_e32 v7, v7, v8
	v_mov_b32_e32 v8, 0x358637bd
	v_fmac_f32_e32 v8, 0x3a800000, v7
	v_rsq_f32_e32 v7, v8
	s_nop 0
	v_mul_f32_e32 v52, v52, v7
	v_mul_f32_e32 v53, v53, v7
	v_mul_f32_e32 v54, v54, v7
	v_mul_f32_e32 v55, v55, v7
	v_mul_f32_e32 v56, v56, v7
	v_mul_f32_e32 v57, v57, v7
	v_mul_f32_e32 v58, v58, v7
	v_mul_f32_e32 v59, v59, v7
	v_mul_f32_e32 v60, v60, v7
	v_mul_f32_e32 v61, v61, v7
	v_mul_f32_e32 v62, v62, v7
	v_mul_f32_e32 v63, v63, v7
	v_mul_f32_e32 v64, v64, v7
	v_mul_f32_e32 v65, v65, v7
	v_mul_f32_e32 v66, v66, v7
	v_mul_f32_e32 v67, v67, v7
	v_add_f32_e32 v100, 1.0, v100
	v_add_f32_e32 v101, 1.0, v101
	v_add_f32_e32 v102, 1.0, v102
	v_add_f32_e32 v103, 1.0, v103
	v_add_f32_e32 v104, 1.0, v104
	v_add_f32_e32 v105, 1.0, v105
	v_add_f32_e32 v106, 1.0, v106
	v_add_f32_e32 v107, 1.0, v107
	v_add_f32_e32 v108, 1.0, v108
	v_add_f32_e32 v109, 1.0, v109
	v_add_f32_e32 v110, 1.0, v110
	v_add_f32_e32 v111, 1.0, v111
	v_add_f32_e32 v112, 1.0, v112
	v_add_f32_e32 v113, 1.0, v113
	v_add_f32_e32 v114, 1.0, v114
	v_add_f32_e32 v115, 1.0, v115
	v_fma_f32 v52, v52, v100, v84
	v_fma_f32 v53, v53, v101, v85
	v_fma_f32 v54, v54, v102, v86
	v_fma_f32 v55, v55, v103, v87
	v_fma_f32 v56, v56, v104, v88
	v_fma_f32 v57, v57, v105, v89
	v_fma_f32 v58, v58, v106, v90
	v_fma_f32 v59, v59, v107, v91
	v_fma_f32 v60, v60, v108, v92
	v_fma_f32 v61, v61, v109, v93
	v_fma_f32 v62, v62, v110, v94
	v_fma_f32 v63, v63, v111, v95
	v_fma_f32 v64, v64, v112, v96
	v_fma_f32 v65, v65, v113, v97
	v_fma_f32 v66, v66, v114, v98
	v_fma_f32 v67, v67, v115, v99
	v_cvt_pk_bf16_f32 v52, v52, v53
	v_cvt_pk_bf16_f32 v53, v54, v55
	v_cvt_pk_bf16_f32 v54, v56, v57
	v_cvt_pk_bf16_f32 v55, v58, v59
	v_cvt_pk_bf16_f32 v56, v60, v61
	v_cvt_pk_bf16_f32 v57, v62, v63
	v_cvt_pk_bf16_f32 v58, v64, v65
	v_cvt_pk_bf16_f32 v59, v66, v67
	global_store_dwordx2 v14, v[52:53], s[26:27] offset:0
	global_store_dwordx2 v14, v[54:55], s[26:27] offset:1024
	global_store_dwordx2 v14, v[56:57], s[26:27] offset:2048
	global_store_dwordx2 v14, v[58:59], s[26:27] offset:3072
	s_mov_b32 s6, s7
	s_branch .Lln0_nextB
; DI bf16 f2bf(float f) { unsigned u = __float_as_uint(f); u += 0x7fffu + ((u >> 16) & 1u); return (bf16)(u >> 16); }
;   DI float* MOD() const { return (float*)(p.ws + WS_MOD); }
;   DI bf16* HY() const { return (bf16*)(p.ws + WS_HY); }
; DI void ln_row(const Ctx& c, int row, int l_post, int l_next, int lane) {
;     ...
;     if (do_h) {
;       float s = 0.f;
; #pragma unroll
;       for (int i = 0; i < 16; ++i) s += v[i];
;       const float mean = wave_sum(s) * (1.f / D);
;       float q = 0.f;
; #pragma unroll
;       for (int i = 0; i < 16; ++i) { v[i] -= mean; q += v[i] * v[i]; }
;       const float rstd = rsqrtf(wave_sum(q) * (1.f / D) + LN_EPS);
;       const float* md = c.MOD() + (l_next * 3 + mod_row(row)) * 3072;
;       bf16* dst = c.HY() + (size_t)row * D;
; #pragma unroll
;       for (int i = 0; i < 4; ++i) {
;         const int col = i * 256 + lane * 4;
;         const float4 sh = *(const float4*)(md + col), sc = *(const float4*)(md + 1024 + col);
;         const float h0 = v[i * 4] * rstd * (1.f + sc.x) + sh.x, h1 = v[i * 4 + 1] * rstd * (1.f + sc.y) + sh.y;
;         const float h2 = v[i * 4 + 2] * rstd * (1.f + sc.z) + sh.z, h3 = v[i * 4 + 3] * rstd * (1.f + sc.w) + sh.w;
;         uint2 pk; pk.x = (unsigned)f2bf(h0) | ((unsigned)f2bf(h1) << 16); pk.y = (unsigned)f2bf(h2) | ((unsigned)f2bf(h3) << 16);
;         *(uint2*)(dst + col) = pk;
;       }
.Lln0_lastA:
	s_waitcnt vmcnt(0)
	s_lshr_b32 s26, s6, 1
	s_lshl_b32 s26, s26, 12
	s_and_b32 s2, s6, 1
	s_lshl_b32 s2, s2, 6
	s_or_b32 s26, s26, s2
	s_add_u32 s26, s88, s26
	s_addc_u32 s27, s89, 0
	s_add_u32 s26, s26, 0x1128000
	s_addc_u32 s27, s27, 0
	v_add_f32_e32 v6, v52, v53
	v_add_f32_e32 v6, v6, v54
	v_add_f32_e32 v6, v6, v55
	v_add_f32_e32 v6, v6, v56
	v_add_f32_e32 v6, v6, v57
	v_add_f32_e32 v6, v6, v58
	v_add_f32_e32 v6, v6, v59
	v_add_f32_e32 v6, v6, v60
	v_add_f32_e32 v6, v6, v61
	v_add_f32_e32 v6, v6, v62
	v_add_f32_e32 v6, v6, v63
	v_add_f32_e32 v6, v6, v64
	v_add_f32_e32 v6, v6, v65
	v_add_f32_e32 v6, v6, v66
	v_add_f32_e32 v6, v6, v67
	s_nop 1
	v_add_f32_dpp v6, v6, v6 row_ror:8 row_mask:0xf bank_mask:0xf bound_ctrl:1
	s_nop 1
	v_add_f32_dpp v6, v6, v6 row_ror:4 row_mask:0xf bank_mask:0xf bound_ctrl:1
	s_nop 1
	v_add_f32_dpp v6, v6, v6 row_ror:2 row_mask:0xf bank_mask:0xf bound_ctrl:1
	s_nop 1
	v_add_f32_dpp v6, v6, v6 row_ror:1 row_mask:0xf bank_mask:0xf bound_ctrl:1
	ds_bpermute_b32 v8, v5, v6
	s_waitcnt lgkmcnt(0)
	v_add_f32_e32 v6, v6, v8
	v_mov_b32_e32 v8, v6
	s_nop 1
	v_permlane32_swap_b32_e32 v6, v8
	v_add_f32_e32 v6, v6, v8
	v_mul_f32_e32 v6, 0x3a800000, v6
	v_sub_f32_e32 v52, v52, v6
	v_sub_f32_e32 v53, v53, v6
	v_sub_f32_e32 v54, v54, v6
	v_sub_f32_e32 v55, v55, v6
	v_sub_f32_e32 v56, v56, v6
	v_sub_f32_e32 v57, v57, v6
	v_sub_f32_e32 v58, v58, v6
	v_sub_f32_e32 v59, v59, v6
	v_sub_f32_e32 v60, v60, v6
	v_sub_f32_e32 v61, v61, v6
	v_sub_f32_e32 v62, v62, v6
	v_sub_f32_e32 v63, v63, v6
	v_sub_f32_e32 v64, v64, v6
	v_sub_f32_e32 v65, v65, v6
	v_sub_f32_e32 v66, v66, v6
	v_sub_f32_e32 v67, v67, v6
	v_mul_f32_e32 v7, v52, v52
	v_fmac_f32_e32 v7, v53, v53
	v_fmac_f32_e32 v7, v54, v54
	v_fmac_f32_e32 v7, v55, v55
	v_fmac_f32_e32 v7, v56, v56
	v_fmac_f32_e32 v7, v57, v57
	v_fmac_f32_e32 v7, v58, v58
	v_fmac_f32_e32 v7, v59, v59
	v_fmac_f32_e32 v7, v60, v60
	v_fmac_f32_e32 v7, v61, v61
	v_fmac_f32_e32 v7, v62, v62
	v_fmac_f32_e32 v7, v63, v63
	v_fmac_f32_e32 v7, v64, v64
	v_fmac_f32_e32 v7, v65, v65
	v_fmac_f32_e32 v7, v66, v66
	v_fmac_f32_e32 v7, v67, v67
	s_nop 1
	v_add_f32_dpp v7, v7, v7 row_ror:8 row_mask:0xf bank_mask:0xf bound_ctrl:1
	s_nop 1
	v_add_f32_dpp v7, v7, v7 row_ror:4 row_mask:0xf bank_mask:0xf bound_ctrl:1
	s_nop 1
	v_add_f32_dpp v7, v7, v7 row_ror:2 row_mask:0xf bank_mask:0xf bound_ctrl:1
	s_nop 1
	v_add_f32_dpp v7, v7, v7 row_ror:1 row_mask:0xf bank_mask:0xf bound_ctrl:1
	ds_bpermute_b32 v8, v5, v7
	s_waitcnt lgkmcnt(0)
	v_add_f32_e32 v7, v7, v8
	v_mov_b32_e32 v8, v7
	s_nop 1
	v_permlane32_swap_b32_e32 v7, v8
	v_add_f32_e32 v7, v7, v8
	v_mov_b32_e32 v8, 0x358637bd
	v_fmac_f32_e32 v8, 0x3a800000, v7
	v_rsq_f32_e32 v7, v8
	s_nop 0
	v_mul_f32_e32 v52, v52, v7
	v_mul_f32_e32 v53, v53, v7
	v_mul_f32_e32 v54, v54, v7
	v_mul_f32_e32 v55, v55, v7
	v_mul_f32_e32 v56, v56, v7
	v_mul_f32_e32 v57, v57, v7
	v_mul_f32_e32 v58, v58, v7
	v_mul_f32_e32 v59, v59, v7
	v_mul_f32_e32 v60, v60, v7
	v_mul_f32_e32 v61, v61, v7
	v_mul_f32_e32 v62, v62, v7
	v_mul_f32_e32 v63, v63, v7
	v_mul_f32_e32 v64, v64, v7
	v_mul_f32_e32 v65, v65, v7
	v_mul_f32_e32 v66, v66, v7
	v_mul_f32_e32 v67, v67, v7
	v_add_f32_e32 v100, 1.0, v100
	v_add_f32_e32 v101, 1.0, v101
	v_add_f32_e32 v102, 1.0, v102
	v_add_f32_e32 v103, 1.0, v103
	v_add_f32_e32 v104, 1.0, v104
	v_add_f32_e32 v105, 1.0, v105
	v_add_f32_e32 v106, 1.0, v106
	v_add_f32_e32 v107, 1.0, v107
	v_add_f32_e32 v108, 1.0, v108
	v_add_f32_e32 v109, 1.0, v109
	v_add_f32_e32 v110, 1.0, v110
	v_add_f32_e32 v111, 1.0, v111
	v_add_f32_e32 v112, 1.0, v112
	v_add_f32_e32 v113, 1.0, v113
	v_add_f32_e32 v114, 1.0, v114
	v_add_f32_e32 v115, 1.0, v115
	v_fma_f32 v52, v52, v100, v84
	v_fma_f32 v53, v53, v101, v85
	v_fma_f32 v54, v54, v102, v86
	v_fma_f32 v55, v55, v103, v87
	v_fma_f32 v56, v56, v104, v88
	v_fma_f32 v57, v57, v105, v89
	v_fma_f32 v58, v58, v106, v90
	v_fma_f32 v59, v59, v107, v91
	v_fma_f32 v60, v60, v108, v92
	v_fma_f32 v61, v61, v109, v93
	v_fma_f32 v62, v62, v110, v94
	v_fma_f32 v63, v63, v111, v95
	v_fma_f32 v64, v64, v112, v96
	v_fma_f32 v65, v65, v113, v97
	v_fma_f32 v66, v66, v114, v98
	v_fma_f32 v67, v67, v115, v99
	v_cvt_pk_bf16_f32 v52, v52, v53
	v_cvt_pk_bf16_f32 v53, v54, v55
	v_cvt_pk_bf16_f32 v54, v56, v57
	v_cvt_pk_bf16_f32 v55, v58, v59
	v_cvt_pk_bf16_f32 v56, v60, v61
	v_cvt_pk_bf16_f32 v57, v62, v63
	v_cvt_pk_bf16_f32 v58, v64, v65
	v_cvt_pk_bf16_f32 v59, v66, v67
	global_store_dwordx2 v14, v[52:53], s[26:27] offset:0
	global_store_dwordx2 v14, v[54:55], s[26:27] offset:1024
	global_store_dwordx2 v14, v[56:57], s[26:27] offset:2048
	global_store_dwordx2 v14, v[58:59], s[26:27] offset:3072
	s_branch .Lln0_exit

; DI bf16 f2bf(float f) { unsigned u = __float_as_uint(f); u += 0x7fffu + ((u >> 16) & 1u); return (bf16)(u >> 16); }
; DI void ln_row(const Ctx& c, int row, int l_post, int l_next, int lane) {
;     ...
;     for (int i = 0; i < 4; ++i) { const float4 t = *(const float4*)(src + i * 256 + lane * 4); v[i * 4] = t.x; v[i * 4 + 1] = t.y; v[i * 4 + 2] = t.z; v[i * 4 + 3] = t.w; }
;     if (do_post) {
;       float s = 0.f;
; #pragma unroll
;       for (int i = 0; i < 16; ++i) s += v[i];
;       const float mean = wave_sum(s) * (1.f / D);
;       float q = 0.f;
; #pragma unroll
;       for (int i = 0; i < 16; ++i) { v[i] -= mean; q += v[i] * v[i]; }
;       const float rstd = rsqrtf(wave_sum(q) * (1.f / D) + LN_EPS);
;       float* dst = c.xrow(row);
; #pragma unroll
;       for (int i = 0; i < 4; ++i) {
;         const int col = i * 256 + lane * 4;
;         const float4 g = *(const float4*)(p.post_g + l_post * D + col), b = *(const float4*)(p.post_b + l_post * D + col);
;         v[i * 4] = v[i * 4] * rstd * g.x + b.x; v[i * 4 + 1] = v[i * 4 + 1] * rstd * g.y + b.y;
;         v[i * 4 + 2] = v[i * 4 + 2] * rstd * g.z + b.z; v[i * 4 + 3] = v[i * 4 + 3] * rstd * g.w + b.w;
;         *(float4*)(dst + col) = make_float4(v[i * 4], v[i * 4 + 1], v[i * 4 + 2], v[i * 4 + 3]);
;       }
;     }
;     if (do_h) {
;       float s = 0.f;
; #pragma unroll
;       for (int i = 0; i < 16; ++i) s += v[i];
;       const float mean = wave_sum(s) * (1.f / D);
;       float q = 0.f;
; #pragma unroll
;       for (int i = 0; i < 16; ++i) { v[i] -= mean; q += v[i] * v[i]; }
;       const float rstd = rsqrtf(wave_sum(q) * (1.f / D) + LN_EPS);
;       const float* md = c.MOD() + (l_next * 3 + mod_row(row)) * 3072;
;       bf16* dst = c.HY() + (size_t)row * D;
; #pragma unroll
;       for (int i = 0; i < 4; ++i) {
;         const int col = i * 256 + lane * 4;
;         const float4 sh = *(const float4*)(md + col), sc = *(const float4*)(md + 1024 + col);
;         const float h0 = v[i * 4] * rstd * (1.f + sc.x) + sh.x, h1 = v[i * 4 + 1] * rstd * (1.f + sc.y) + sh.y;
;         const float h2 = v[i * 4 + 2] * rstd * (1.f + sc.z) + sh.z, h3 = v[i * 4 + 3] * rstd * (1.f + sc.w) + sh.w;
;         uint2 pk; pk.x = (unsigned)f2bf(h0) | ((unsigned)f2bf(h1) << 16); pk.y = (unsigned)f2bf(h2) | ((unsigned)f2bf(h3) << 16);
;         *(uint2*)(dst + col) = pk;
;       }
.Lln0_j2:
	global_load_dwordx4 v[52:55], v2, s[2:3] offset:0
	global_load_dwordx4 v[56:59], v2, s[2:3] offset:1024
	global_load_dwordx4 v[60:63], v2, s[2:3] offset:2048
	global_load_dwordx4 v[64:67], v2, s[2:3] offset:3072
	s_add_u32 s8, s8, s20
	s_mul_i32 s8, s8, 0x3000
	s_add_u32 s10, s88, s8
	s_addc_u32 s11, s89, 0
	s_add_u32 s10, s10, 0x4000
	s_addc_u32 s11, s11, 0
	global_load_dwordx4 v[84:87], v2, s[10:11] offset:0
	global_load_dwordx4 v[88:91], v2, s[10:11] offset:1024
	global_load_dwordx4 v[92:95], v2, s[10:11] offset:2048
	global_load_dwordx4 v[96:99], v2, s[10:11] offset:3072
	s_add_u32 s10, s10, 0x1000
	s_addc_u32 s11, s11, 0
	global_load_dwordx4 v[100:103], v2, s[10:11] offset:0
	global_load_dwordx4 v[104:107], v2, s[10:11] offset:1024
	global_load_dwordx4 v[108:111], v2, s[10:11] offset:2048
	global_load_dwordx4 v[112:115], v2, s[10:11] offset:3072
	s_waitcnt vmcnt(12)
	s_lshr_b32 s26, s6, 1
	s_lshl_b32 s26, s26, 12
	s_and_b32 s2, s6, 1
	s_lshl_b32 s2, s2, 6
	s_or_b32 s26, s26, s2
	s_add_u32 s26, s88, s26
	s_addc_u32 s27, s89, 0
	s_add_u32 s26, s26, 0x1128000
	s_addc_u32 s27, s27, 0
	v_add_f32_e32 v6, v68, v69
	v_add_f32_e32 v6, v6, v70
	v_add_f32_e32 v6, v6, v71
	v_add_f32_e32 v6, v6, v72
	v_add_f32_e32 v6, v6, v73
	v_add_f32_e32 v6, v6, v74
	v_add_f32_e32 v6, v6, v75
	v_add_f32_e32 v6, v6, v76
	v_add_f32_e32 v6, v6, v77
	v_add_f32_e32 v6, v6, v78
	v_add_f32_e32 v6, v6, v79
	v_add_f32_e32 v6, v6, v80
	v_add_f32_e32 v6, v6, v81
	v_add_f32_e32 v6, v6, v82
	v_add_f32_e32 v6, v6, v83
	s_nop 1
	v_add_f32_dpp v6, v6, v6 row_ror:8 row_mask:0xf bank_mask:0xf bound_ctrl:1
	s_nop 1
	v_add_f32_dpp v6, v6, v6 row_ror:4 row_mask:0xf bank_mask:0xf bound_ctrl:1
	s_nop 1
	v_add_f32_dpp v6, v6, v6 row_ror:2 row_mask:0xf bank_mask:0xf bound_ctrl:1
	s_nop 1
	v_add_f32_dpp v6, v6, v6 row_ror:1 row_mask:0xf bank_mask:0xf bound_ctrl:1
	ds_bpermute_b32 v8, v5, v6
	s_waitcnt lgkmcnt(0)
	v_add_f32_e32 v6, v6, v8
	v_mov_b32_e32 v8, v6
	s_nop 1
	v_permlane32_swap_b32_e32 v6, v8
	v_add_f32_e32 v6, v6, v8
	v_mul_f32_e32 v6, 0x3a800000, v6
	v_sub_f32_e32 v68, v68, v6
	v_sub_f32_e32 v69, v69, v6
	v_sub_f32_e32 v70, v70, v6
	v_sub_f32_e32 v71, v71, v6
	v_sub_f32_e32 v72, v72, v6
	v_sub_f32_e32 v73, v73, v6
	v_sub_f32_e32 v74, v74, v6
	v_sub_f32_e32 v75, v75, v6
	v_sub_f32_e32 v76, v76, v6
	v_sub_f32_e32 v77, v77, v6
	v_sub_f32_e32 v78, v78, v6
	v_sub_f32_e32 v79, v79, v6
	v_sub_f32_e32 v80, v80, v6
	v_sub_f32_e32 v81, v81, v6
	v_sub_f32_e32 v82, v82, v6
	v_sub_f32_e32 v83, v83, v6
	v_mul_f32_e32 v7, v68, v68
	v_fmac_f32_e32 v7, v69, v69
	v_fmac_f32_e32 v7, v70, v70
	v_fmac_f32_e32 v7, v71, v71
	v_fmac_f32_e32 v7, v72, v72
	v_fmac_f32_e32 v7, v73, v73
	v_fmac_f32_e32 v7, v74, v74
	v_fmac_f32_e32 v7, v75, v75
	v_fmac_f32_e32 v7, v76, v76
	v_fmac_f32_e32 v7, v77, v77
	v_fmac_f32_e32 v7, v78, v78
	v_fmac_f32_e32 v7, v79, v79
	v_fmac_f32_e32 v7, v80, v80
	v_fmac_f32_e32 v7, v81, v81
	v_fmac_f32_e32 v7, v82, v82
	v_fmac_f32_e32 v7, v83, v83
	s_nop 1
	v_add_f32_dpp v7, v7, v7 row_ror:8 row_mask:0xf bank_mask:0xf bound_ctrl:1
	s_nop 1
	v_add_f32_dpp v7, v7, v7 row_ror:4 row_mask:0xf bank_mask:0xf bound_ctrl:1
	s_nop 1
	v_add_f32_dpp v7, v7, v7 row_ror:2 row_mask:0xf bank_mask:0xf bound_ctrl:1
	s_nop 1
	v_add_f32_dpp v7, v7, v7 row_ror:1 row_mask:0xf bank_mask:0xf bound_ctrl:1
	ds_bpermute_b32 v8, v5, v7
	s_waitcnt lgkmcnt(0)
	v_add_f32_e32 v7, v7, v8
	v_mov_b32_e32 v8, v7
	s_nop 1
	v_permlane32_swap_b32_e32 v7, v8
	v_add_f32_e32 v7, v7, v8
	v_mov_b32_e32 v8, 0x358637bd
	v_fmac_f32_e32 v8, 0x3a800000, v7
	v_rsq_f32_e32 v7, v8
	s_nop 0
	v_mul_f32_e32 v68, v68, v7
	v_mul_f32_e32 v69, v69, v7
	v_mul_f32_e32 v70, v70, v7
	v_mul_f32_e32 v71, v71, v7
	v_mul_f32_e32 v72, v72, v7
	v_mul_f32_e32 v73, v73, v7
	v_mul_f32_e32 v74, v74, v7
	v_mul_f32_e32 v75, v75, v7
	v_mul_f32_e32 v76, v76, v7
	v_mul_f32_e32 v77, v77, v7
	v_mul_f32_e32 v78, v78, v7
	v_mul_f32_e32 v79, v79, v7
	v_mul_f32_e32 v80, v80, v7
	v_mul_f32_e32 v81, v81, v7
	v_mul_f32_e32 v82, v82, v7
	v_mul_f32_e32 v83, v83, v7
	v_add_f32_e32 v132, 1.0, v132
	v_add_f32_e32 v133, 1.0, v133
	v_add_f32_e32 v134, 1.0, v134
	v_add_f32_e32 v135, 1.0, v135
	v_add_f32_e32 v136, 1.0, v136
	v_add_f32_e32 v137, 1.0, v137
	v_add_f32_e32 v138, 1.0, v138
	v_add_f32_e32 v139, 1.0, v139
	v_add_f32_e32 v140, 1.0, v140
	v_add_f32_e32 v141, 1.0, v141
	v_add_f32_e32 v142, 1.0, v142
	v_add_f32_e32 v143, 1.0, v143
	v_add_f32_e32 v144, 1.0, v144
	v_add_f32_e32 v145, 1.0, v145
	v_add_f32_e32 v146, 1.0, v146
	v_add_f32_e32 v147, 1.0, v147
	v_fma_f32 v68, v68, v132, v116
	v_fma_f32 v69, v69, v133, v117
	v_fma_f32 v70, v70, v134, v118
	v_fma_f32 v71, v71, v135, v119
	v_fma_f32 v72, v72, v136, v120
	v_fma_f32 v73, v73, v137, v121
	v_fma_f32 v74, v74, v138, v122
	v_fma_f32 v75, v75, v139, v123
	v_fma_f32 v76, v76, v140, v124
	v_fma_f32 v77, v77, v141, v125
	v_fma_f32 v78, v78, v142, v126
	v_fma_f32 v79, v79, v143, v127
	v_fma_f32 v80, v80, v144, v128
	v_fma_f32 v81, v81, v145, v129
	v_fma_f32 v82, v82, v146, v130
	v_fma_f32 v83, v83, v147, v131
	v_cvt_pk_bf16_f32 v68, v68, v69
	v_cvt_pk_bf16_f32 v69, v70, v71
	v_cvt_pk_bf16_f32 v70, v72, v73
	v_cvt_pk_bf16_f32 v71, v74, v75
	v_cvt_pk_bf16_f32 v72, v76, v77
	v_cvt_pk_bf16_f32 v73, v78, v79
	v_cvt_pk_bf16_f32 v74, v80, v81
	v_cvt_pk_bf16_f32 v75, v82, v83
	global_store_dwordx2 v14, v[68:69], s[26:27] offset:0
	global_store_dwordx2 v14, v[70:71], s[26:27] offset:1024
	global_store_dwordx2 v14, v[72:73], s[26:27] offset:2048
	global_store_dwordx2 v14, v[74:75], s[26:27] offset:3072
	s_mov_b32 s6, s7
	s_branch .Lln0_loop
; DI bf16 f2bf(float f) { unsigned u = __float_as_uint(f); u += 0x7fffu + ((u >> 16) & 1u); return (bf16)(u >> 16); }
;   DI float* MOD() const { return (float*)(p.ws + WS_MOD); }
;   DI bf16* HY() const { return (bf16*)(p.ws + WS_HY); }
; DI void ln_row(const Ctx& c, int row, int l_post, int l_next, int lane) {
;     ...
;     if (do_h) {
;       float s = 0.f;
; #pragma unroll
;       for (int i = 0; i < 16; ++i) s += v[i];
;       const float mean = wave_sum(s) * (1.f / D);
;       float q = 0.f;
; #pragma unroll
;       for (int i = 0; i < 16; ++i) { v[i] -= mean; q += v[i] * v[i]; }
;       const float rstd = rsqrtf(wave_sum(q) * (1.f / D) + LN_EPS);
;       const float* md = c.MOD() + (l_next * 3 + mod_row(row)) * 3072;
;       bf16* dst = c.HY() + (size_t)row * D;
; #pragma unroll
;       for (int i = 0; i < 4; ++i) {
;         const int col = i * 256 + lane * 4;
;         const float4 sh = *(const float4*)(md + col), sc = *(const float4*)(md + 1024 + col);
;         const float h0 = v[i * 4] * rstd * (1.f + sc.x) + sh.x, h1 = v[i * 4 + 1] * rstd * (1.f + sc.y) + sh.y;
;         const float h2 = v[i * 4 + 2] * rstd * (1.f + sc.z) + sh.z, h3 = v[i * 4 + 3] * rstd * (1.f + sc.w) + sh.w;
;         uint2 pk; pk.x = (unsigned)f2bf(h0) | ((unsigned)f2bf(h1) << 16); pk.y = (unsigned)f2bf(h2) | ((unsigned)f2bf(h3) << 16);
;         *(uint2*)(dst + col) = pk;
;       }
.Lln0_lastB:
	s_waitcnt vmcnt(0)
	s_lshr_b32 s26, s6, 1
	s_lshl_b32 s26, s26, 12
	s_and_b32 s2, s6, 1
	s_lshl_b32 s2, s2, 6
	s_or_b32 s26, s26, s2
	s_add_u32 s26, s88, s26
	s_addc_u32 s27, s89, 0
	s_add_u32 s26, s26, 0x1128000
	s_addc_u32 s27, s27, 0
	v_add_f32_e32 v6, v68, v69
	v_add_f32_e32 v6, v6, v70
	v_add_f32_e32 v6, v6, v71
	v_add_f32_e32 v6, v6, v72
	v_add_f32_e32 v6, v6, v73
	v_add_f32_e32 v6, v6, v74
	v_add_f32_e32 v6, v6, v75
	v_add_f32_e32 v6, v6, v76
	v_add_f32_e32 v6, v6, v77
	v_add_f32_e32 v6, v6, v78
	v_add_f32_e32 v6, v6, v79
	v_add_f32_e32 v6, v6, v80
	v_add_f32_e32 v6, v6, v81
	v_add_f32_e32 v6, v6, v82
	v_add_f32_e32 v6, v6, v83
	s_nop 1
	v_add_f32_dpp v6, v6, v6 row_ror:8 row_mask:0xf bank_mask:0xf bound_ctrl:1
	s_nop 1
	v_add_f32_dpp v6, v6, v6 row_ror:4 row_mask:0xf bank_mask:0xf bound_ctrl:1
	s_nop 1
	v_add_f32_dpp v6, v6, v6 row_ror:2 row_mask:0xf bank_mask:0xf bound_ctrl:1
	s_nop 1
	v_add_f32_dpp v6, v6, v6 row_ror:1 row_mask:0xf bank_mask:0xf bound_ctrl:1
	ds_bpermute_b32 v8, v5, v6
	s_waitcnt lgkmcnt(0)
	v_add_f32_e32 v6, v6, v8
	v_mov_b32_e32 v8, v6
	s_nop 1
	v_permlane32_swap_b32_e32 v6, v8
	v_add_f32_e32 v6, v6, v8
	v_mul_f32_e32 v6, 0x3a800000, v6
	v_sub_f32_e32 v68, v68, v6
	v_sub_f32_e32 v69, v69, v6
	v_sub_f32_e32 v70, v70, v6
	v_sub_f32_e32 v71, v71, v6
	v_sub_f32_e32 v72, v72, v6
	v_sub_f32_e32 v73, v73, v6
	v_sub_f32_e32 v74, v74, v6
	v_sub_f32_e32 v75, v75, v6
	v_sub_f32_e32 v76, v76, v6
	v_sub_f32_e32 v77, v77, v6
	v_sub_f32_e32 v78, v78, v6
	v_sub_f32_e32 v79, v79, v6
	v_sub_f32_e32 v80, v80, v6
	v_sub_f32_e32 v81, v81, v6
	v_sub_f32_e32 v82, v82, v6
	v_sub_f32_e32 v83, v83, v6
	v_mul_f32_e32 v7, v68, v68
	v_fmac_f32_e32 v7, v69, v69
	v_fmac_f32_e32 v7, v70, v70
	v_fmac_f32_e32 v7, v71, v71
	v_fmac_f32_e32 v7, v72, v72
	v_fmac_f32_e32 v7, v73, v73
	v_fmac_f32_e32 v7, v74, v74
	v_fmac_f32_e32 v7, v75, v75
	v_fmac_f32_e32 v7, v76, v76
	v_fmac_f32_e32 v7, v77, v77
	v_fmac_f32_e32 v7, v78, v78
	v_fmac_f32_e32 v7, v79, v79
	v_fmac_f32_e32 v7, v80, v80
	v_fmac_f32_e32 v7, v81, v81
	v_fmac_f32_e32 v7, v82, v82
	v_fmac_f32_e32 v7, v83, v83
	s_nop 1
	v_add_f32_dpp v7, v7, v7 row_ror:8 row_mask:0xf bank_mask:0xf bound_ctrl:1
	s_nop 1
	v_add_f32_dpp v7, v7, v7 row_ror:4 row_mask:0xf bank_mask:0xf bound_ctrl:1
	s_nop 1
	v_add_f32_dpp v7, v7, v7 row_ror:2 row_mask:0xf bank_mask:0xf bound_ctrl:1
	s_nop 1
	v_add_f32_dpp v7, v7, v7 row_ror:1 row_mask:0xf bank_mask:0xf bound_ctrl:1
	ds_bpermute_b32 v8, v5, v7
	s_waitcnt lgkmcnt(0)
	v_add_f32_e32 v7, v7, v8
	v_mov_b32_e32 v8, v7
	s_nop 1
	v_permlane32_swap_b32_e32 v7, v8
	v_add_f32_e32 v7, v7, v8
	v_mov_b32_e32 v8, 0x358637bd
	v_fmac_f32_e32 v8, 0x3a800000, v7
	v_rsq_f32_e32 v7, v8
	s_nop 0
	v_mul_f32_e32 v68, v68, v7
	v_mul_f32_e32 v69, v69, v7
	v_mul_f32_e32 v70, v70, v7
	v_mul_f32_e32 v71, v71, v7
	v_mul_f32_e32 v72, v72, v7
	v_mul_f32_e32 v73, v73, v7
	v_mul_f32_e32 v74, v74, v7
	v_mul_f32_e32 v75, v75, v7
	v_mul_f32_e32 v76, v76, v7
	v_mul_f32_e32 v77, v77, v7
	v_mul_f32_e32 v78, v78, v7
	v_mul_f32_e32 v79, v79, v7
	v_mul_f32_e32 v80, v80, v7
	v_mul_f32_e32 v81, v81, v7
	v_mul_f32_e32 v82, v82, v7
	v_mul_f32_e32 v83, v83, v7
	v_add_f32_e32 v132, 1.0, v132
	v_add_f32_e32 v133, 1.0, v133
	v_add_f32_e32 v134, 1.0, v134
	v_add_f32_e32 v135, 1.0, v135
	v_add_f32_e32 v136, 1.0, v136
	v_add_f32_e32 v137, 1.0, v137
	v_add_f32_e32 v138, 1.0, v138
	v_add_f32_e32 v139, 1.0, v139
	v_add_f32_e32 v140, 1.0, v140
	v_add_f32_e32 v141, 1.0, v141
	v_add_f32_e32 v142, 1.0, v142
	v_add_f32_e32 v143, 1.0, v143
	v_add_f32_e32 v144, 1.0, v144
	v_add_f32_e32 v145, 1.0, v145
	v_add_f32_e32 v146, 1.0, v146
	v_add_f32_e32 v147, 1.0, v147
	v_fma_f32 v68, v68, v132, v116
	v_fma_f32 v69, v69, v133, v117
	v_fma_f32 v70, v70, v134, v118
	v_fma_f32 v71, v71, v135, v119
	v_fma_f32 v72, v72, v136, v120
	v_fma_f32 v73, v73, v137, v121
	v_fma_f32 v74, v74, v138, v122
	v_fma_f32 v75, v75, v139, v123
	v_fma_f32 v76, v76, v140, v124
	v_fma_f32 v77, v77, v141, v125
	v_fma_f32 v78, v78, v142, v126
	v_fma_f32 v79, v79, v143, v127
	v_fma_f32 v80, v80, v144, v128
	v_fma_f32 v81, v81, v145, v129
	v_fma_f32 v82, v82, v146, v130
	v_fma_f32 v83, v83, v147, v131
	v_cvt_pk_bf16_f32 v68, v68, v69
	v_cvt_pk_bf16_f32 v69, v70, v71
	v_cvt_pk_bf16_f32 v70, v72, v73
	v_cvt_pk_bf16_f32 v71, v74, v75
	v_cvt_pk_bf16_f32 v72, v76, v77
	v_cvt_pk_bf16_f32 v73, v78, v79
	v_cvt_pk_bf16_f32 v74, v80, v81
	v_cvt_pk_bf16_f32 v75, v82, v83
	global_store_dwordx2 v14, v[68:69], s[26:27] offset:0
	global_store_dwordx2 v14, v[70:71], s[26:27] offset:1024
	global_store_dwordx2 v14, v[72:73], s[26:27] offset:2048
	global_store_dwordx2 v14, v[74:75], s[26:27] offset:3072
	s_branch .Lln0_exit

; DI int otid() { int t = threadIdx.x; asm volatile("" : "+v"(t)); return t; }
;   DI bf16* K() const { return (bf16*)(p.ws + WS_K); }
; template <class AP, class BP, class Epi>
; DI void mfma_gemm_big_tile(const AP& aptr, const BP& bptr, int m0, int n0, int K, const Epi& epi, bf16* lds) {
;   const int tid = otid(), lane = tid & 63, wave = __builtin_amdgcn_readfirstlane(tid >> 6);
;   const int wm = (wave >> 1) * 128, wn = (wave & 1) * 64;
;   const int l16 = lane & 15, lq = lane >> 4;
;   const int lrow = tid >> 2, lcol = ((tid & 3) ^ ((-(tid >> 4)) & 3)) * 8;
;   const bf16* ap[4]; const bf16* bp[2];
; #pragma unroll
;   for (int i = 0; i < 4; ++i) ap[i] = aptr(m0 + lrow + 64 * i) + lcol;
; #pragma unroll
;   for (int i = 0; i < 2; ++i) bp[i] = bptr(n0 + lrow + 64 * i) + lcol;
;   f32x4 acc[8][4];
; #pragma unroll
;   for (int i = 0; i < 8; ++i)
; #pragma unroll
;     for (int j = 0; j < 4; ++j) acc[i][j] = f32x4{0.f, 0.f, 0.f, 0.f};
;   const int nk = K >> 5;
;     ...
;   BG_ISSUE(0, 0);
;   BG_ISSUE(1, 1);
; template <class AP, class BP, class Epi>
; DI void mfma_gemm_big(const AP& aptr, const BP& bptr, int M, int N, int K, const Epi& epi, bf16* lds) {
;   const int tn = N / 128, tiles = (M / 256) * tn;
;   xcd_items(tiles, [&](int t) { mfma_gemm_big_tile(aptr, bptr, (t / tn) * 256, (t % tn) * 128, K, epi, lds); });
.LBB0_248:
	s_mul_i32 s0, s8, s2
	s_add_i32 s0, s9, s0
	s_mul_hi_i32 s1, s0, 0x66666667
	s_lshr_b32 s4, s1, 31
	s_ashr_i32 s1, s1, 3
	v_mov_b32_e32 v26, v172
	s_add_i32 s1, s1, s4
	s_lshl_b32 s10, s1, 8
	v_lshrrev_b32_e32 v142, 4, v26
	s_mul_i32 s1, s1, 20
	v_sub_u32_e32 v27, 0, v142
	s_sub_i32 s0, s0, s1
	v_ashrrev_i32_e32 v18, 2, v26
	v_xor_b32_e32 v0, v26, v27
	s_lshl_b32 s11, s0, 7
	v_readfirstlane_b32 s0, v26
	v_add_u32_e32 v2, s10, v18
	v_lshlrev_b32_e32 v0, 4, v0
	s_and_b32 s12, s0, 64
	v_and_b32_e32 v0, 48, v0
	v_ashrrev_i32_e32 v3, 31, v2
	v_add_u32_e32 v10, 64, v2
	s_and_b32 s17, s0, 0xffffff80
	s_lshl_b32 s0, s0, 4
	v_lshl_add_u64 v[4:5], s[60:61], 0, v[0:1]
	v_bfe_u32 v30, v26, 2, 1
	v_mul_i32_i24_e32 v30, 0xfffff840, v30
	v_ashrrev_i32_e32 v31, 31, v30
	v_lshl_add_u64 v[4:5], v[4:5], 0, v[30:31]
	v_lshlrev_b64 v[6:7], 11, v[2:3]
	v_ashrrev_i32_e32 v11, 31, v10
	v_add_u32_e32 v14, 0x80, v2
	s_and_b32 s18, s0, 0xfffffc00
	v_lshl_add_u64 v[8:9], v[4:5], 0, v[6:7]
	v_lshlrev_b64 v[10:11], 11, v[10:11]
	v_ashrrev_i32_e32 v15, 31, v14
	v_add_u32_e32 v2, 0xc0, v2
	v_add_u32_e32 v18, s11, v18
	s_mov_b32 m0, s18
	v_lshl_add_u64 v[12:13], v[4:5], 0, v[10:11]
	v_lshlrev_b64 v[14:15], 11, v[14:15]
	v_ashrrev_i32_e32 v3, 31, v2
	v_ashrrev_i32_e32 v19, 31, v18
	global_load_lds_dwordx4 v[8:9], off
	s_add_i32 m0, s18, 0x1000
	v_lshl_add_u64 v[16:17], v[4:5], 0, v[14:15]
	v_lshlrev_b64 v[2:3], 11, v[2:3]
	v_lshlrev_b64 v[22:23], 11, v[18:19]
	v_add_u32_e32 v18, 64, v18
	global_load_lds_dwordx4 v[12:13], off
	s_add_i32 m0, s18, 0x2000
	v_lshl_add_u64 v[4:5], v[4:5], 0, v[2:3]
	v_lshl_add_u64 v[20:21], s[52:53], 0, v[0:1]
	v_ashrrev_i32_e32 v19, 31, v18
	global_load_lds_dwordx4 v[16:17], off
	s_add_i32 m0, s18, 0x3000
	v_lshl_add_u64 v[24:25], v[20:21], 0, v[22:23]
	v_lshlrev_b64 v[18:19], 11, v[18:19]
	global_load_lds_dwordx4 v[4:5], off
	s_add_i32 m0, s18, 0x4000
	v_lshl_add_u64 v[20:21], v[20:21], 0, v[18:19]
	global_load_lds_dwordx4 v[24:25], off
	s_add_i32 m0, s18, 0x5000
	v_lshl_add_u64 v[8:9], v[8:9], 0, 64
	v_lshl_add_u64 v[8:9], v[8:9], 0, 64
	global_load_lds_dwordx4 v[20:21], off
	s_add_i32 m0, s18, 0x6000
	v_lshl_add_u64 v[4:5], v[4:5], 0, 64
	v_lshl_add_u64 v[4:5], v[4:5], 0, 64
	global_load_lds_dwordx4 v[8:9], off
	v_lshl_add_u64 v[8:9], v[12:13], 0, 64
	v_lshl_add_u64 v[8:9], v[8:9], 0, 64
	s_add_i32 m0, s18, 0x7000
	v_and_b32_e32 v0, 15, v26
	global_load_lds_dwordx4 v[8:9], off
	v_lshl_add_u64 v[8:9], v[16:17], 0, 64
	v_lshl_add_u64 v[8:9], v[8:9], 0, 64
	s_add_i32 m0, s18, 0x8000
	v_readlane_b32 s0, v253, 53
	global_load_lds_dwordx4 v[8:9], off
	s_add_i32 m0, s18, 0x9000
	v_readlane_b32 s1, v253, 54
	global_load_lds_dwordx4 v[4:5], off
	v_lshl_add_u64 v[4:5], v[24:25], 0, 64
	s_add_i32 m0, s18, 0xa000
	s_mov_b32 s13, 2
	global_load_lds_dwordx4 v[4:5], off
	v_lshl_add_u64 v[4:5], v[20:21], 0, 64
	s_add_i32 m0, s18, 0xb000
	s_mov_b32 s16, 0
	global_load_lds_dwordx4 v[4:5], off
	v_lshrrev_b32_e32 v5, 2, v26
	v_sub_u32_e32 v5, 0, v5
	v_xor_b32_e32 v5, v142, v5
	v_lshlrev_b32_e32 v5, 4, v5
	v_or_b32_e32 v4, s17, v0
	v_and_b32_e32 v5, 48, v5
	v_lshl_or_b32 v143, v4, 6, v5
	v_or_b32_e32 v4, s12, v0
	v_lshlrev_b32_e32 v4, 6, v4
	v_or3_b32 v144, v5, v4, s77
	v_bitop3_b32 v4, v26, 3, v27 bitop3:0x48
	v_lshlrev_b32_e32 v4, 4, v4
	v_or_b32_e32 v18, v18, v4
	v_or_b32_e32 v22, v22, v4
	v_lshl_add_u64 v[130:131], s[0:1], 0, v[18:19]
	v_lshl_add_u64 v[132:133], s[0:1], 0, v[22:23]
	v_readlane_b32 s0, v253, 55
	s_waitcnt vmcnt(6)
	s_barrier
;   DI bf16* K() const { return (bf16*)(p.ws + WS_K); }
; template <class AP, class BP, class Epi>
; DI void mfma_gemm_big_tile(const AP& aptr, const BP& bptr, int m0, int n0, int K, const Epi& epi, bf16* lds) {
;     ...
;   const bf16* ap[4]; const bf16* bp[2];
; #pragma unroll
;   for (int i = 0; i < 4; ++i) ap[i] = aptr(m0 + lrow + 64 * i) + lcol;
; #pragma unroll
;   for (int i = 0; i < 2; ++i) bp[i] = bptr(n0 + lrow + 64 * i) + lcol;
;   f32x4 acc[8][4];
; #pragma unroll
;   for (int i = 0; i < 8; ++i)
; #pragma unroll
;     for (int j = 0; j < 4; ++j) acc[i][j] = f32x4{0.f, 0.f, 0.f, 0.f};
;   const int nk = K >> 5;
	v_or_b32_e32 v2, v2, v4
	v_readlane_b32 s1, v253, 56
	v_or_b32_e32 v14, v14, v4
	v_or_b32_e32 v10, v10, v4
	v_lshl_add_u64 v[134:135], s[0:1], 0, v[2:3]
	v_or_b32_e32 v6, v6, v4
	v_mov_b32_e32 v2, 0
	v_lshl_add_u64 v[136:137], s[0:1], 0, v[14:15]
	v_lshl_add_u64 v[138:139], s[0:1], 0, v[10:11]
	v_lshl_add_u64 v[140:141], s[0:1], 0, v[6:7]
	v_lshl_add_u64 v[30:31], v[30:31], 0, 64
	v_lshl_add_u64 v[30:31], v[30:31], 0, 64
	v_lshl_add_u64 v[134:135], v[134:135], 0, v[30:31]
	v_lshl_add_u64 v[136:137], v[136:137], 0, v[30:31]
	v_lshl_add_u64 v[138:139], v[138:139], 0, v[30:31]
	v_lshl_add_u64 v[140:141], v[140:141], 0, v[30:31]
	s_mov_b64 s[0:1], 0
	s_mov_b32 s19, 0
	v_mov_b32_e32 v3, v2
	v_mov_b32_e32 v4, v2
	v_mov_b32_e32 v5, v2
	v_mov_b32_e32 v6, v2
	v_mov_b32_e32 v7, v2
	v_mov_b32_e32 v8, v2
	v_mov_b32_e32 v9, v2
	v_mov_b32_e32 v10, v2
	v_mov_b32_e32 v11, v2
	v_mov_b32_e32 v12, v2
	v_mov_b32_e32 v13, v2
	v_mov_b32_e32 v14, v2
	v_mov_b32_e32 v15, v2
	v_mov_b32_e32 v16, v2
	v_mov_b32_e32 v17, v2
	v_mov_b32_e32 v18, v2
	v_mov_b32_e32 v19, v2
	v_mov_b32_e32 v20, v2
	v_mov_b32_e32 v21, v2
	v_mov_b32_e32 v22, v2
	v_mov_b32_e32 v23, v2
	v_mov_b32_e32 v24, v2
	v_mov_b32_e32 v25, v2
	v_mov_b32_e32 v26, v2
	v_mov_b32_e32 v27, v2
	v_mov_b32_e32 v28, v2
	v_mov_b32_e32 v29, v2
	v_mov_b32_e32 v30, v2
	v_mov_b32_e32 v31, v2
	v_mov_b32_e32 v32, v2
	v_mov_b32_e32 v33, v2
	v_mov_b32_e32 v34, v2
	v_mov_b32_e32 v35, v2
	v_mov_b32_e32 v36, v2
	v_mov_b32_e32 v37, v2
	v_mov_b32_e32 v38, v2
	v_mov_b32_e32 v39, v2
	v_mov_b32_e32 v40, v2
	v_mov_b32_e32 v41, v2
	v_mov_b32_e32 v42, v2
	v_mov_b32_e32 v43, v2
	v_mov_b32_e32 v44, v2
	v_mov_b32_e32 v45, v2
	v_mov_b32_e32 v46, v2
	v_mov_b32_e32 v47, v2
	v_mov_b32_e32 v48, v2
	v_mov_b32_e32 v49, v2
	v_mov_b32_e32 v50, v2
	v_mov_b32_e32 v51, v2
	v_mov_b32_e32 v52, v2
	v_mov_b32_e32 v53, v2
	v_mov_b32_e32 v54, v2
	v_mov_b32_e32 v55, v2
	v_mov_b32_e32 v56, v2
	v_mov_b32_e32 v57, v2
	v_mov_b32_e32 v58, v2
	v_mov_b32_e32 v59, v2
	v_mov_b32_e32 v60, v2
	v_mov_b32_e32 v61, v2
	v_mov_b32_e32 v62, v2
	v_mov_b32_e32 v63, v2
	v_mov_b32_e32 v64, v2
	v_mov_b32_e32 v65, v2
	v_mov_b32_e32 v66, v2
	v_mov_b32_e32 v67, v2
	v_mov_b32_e32 v68, v2
	v_mov_b32_e32 v69, v2
	v_mov_b32_e32 v70, v2
	v_mov_b32_e32 v71, v2
	v_mov_b32_e32 v72, v2
	v_mov_b32_e32 v73, v2
	v_mov_b32_e32 v74, v2
	v_mov_b32_e32 v75, v2
	v_mov_b32_e32 v76, v2
	v_mov_b32_e32 v77, v2
	v_mov_b32_e32 v78, v2
	v_mov_b32_e32 v79, v2
	v_mov_b32_e32 v80, v2
	v_mov_b32_e32 v81, v2
	v_mov_b32_e32 v82, v2
	v_mov_b32_e32 v83, v2
	v_mov_b32_e32 v84, v2
	v_mov_b32_e32 v85, v2
	v_mov_b32_e32 v86, v2
	v_mov_b32_e32 v87, v2
	v_mov_b32_e32 v88, v2
	v_mov_b32_e32 v89, v2
	v_mov_b32_e32 v90, v2
	v_mov_b32_e32 v91, v2
	v_mov_b32_e32 v92, v2
	v_mov_b32_e32 v93, v2
	v_mov_b32_e32 v94, v2
	v_mov_b32_e32 v95, v2
	v_mov_b32_e32 v96, v2
	v_mov_b32_e32 v97, v2
	v_mov_b32_e32 v98, v2
	v_mov_b32_e32 v99, v2
	v_mov_b32_e32 v100, v2
	v_mov_b32_e32 v101, v2
	v_mov_b32_e32 v102, v2
	v_mov_b32_e32 v103, v2
	v_mov_b32_e32 v104, v2
	v_mov_b32_e32 v105, v2
	v_mov_b32_e32 v106, v2
	v_mov_b32_e32 v107, v2
	v_mov_b32_e32 v108, v2
	v_mov_b32_e32 v109, v2
	v_mov_b32_e32 v110, v2
	v_mov_b32_e32 v111, v2
	v_mov_b32_e32 v112, v2
	v_mov_b32_e32 v113, v2
	v_mov_b32_e32 v114, v2
	v_mov_b32_e32 v115, v2
	v_mov_b32_e32 v116, v2
	v_mov_b32_e32 v117, v2
	v_mov_b32_e32 v118, v2
	v_mov_b32_e32 v119, v2
	v_mov_b32_e32 v120, v2
	v_mov_b32_e32 v121, v2
	v_mov_b32_e32 v122, v2
	v_mov_b32_e32 v123, v2
	v_mov_b32_e32 v124, v2
	v_mov_b32_e32 v125, v2
	v_mov_b32_e32 v126, v2
	v_mov_b32_e32 v127, v2
	v_mov_b32_e32 v128, v2
	v_mov_b32_e32 v129, v2
	s_branch .LBB0_250

; template <class AP, class BP, class Epi>
; DI void mfma_gemm_big_tile(const AP& aptr, const BP& bptr, int m0, int n0, int K, const Epi& epi, bf16* lds) {
;     ...
;   BG_ISSUE(0, 0);
;   BG_ISSUE(1, 1);
;   asm volatile("s_waitcnt vmcnt(6)\n\ts_barrier" ::: "memory");
;   const unsigned lbase = (unsigned)(size_t)lds;
;   const unsigned a_off = (unsigned)(((wm + l16) * 32 + (lq ^ ((-(l16 >> 2)) & 3)) * 8) * 2);
;   const unsigned b_off = (unsigned)((256 * 32 + (wn + l16) * 32 + (lq ^ ((-(l16 >> 2)) & 3)) * 8) * 2);
;     ...
;   int cur = 0, nxt = 2;
;   for (int ks = 0; ks < nk; ++ks) {
;     if (ks + 2 < nk) BG_ISSUE(nxt, ks + 2);
.LBB0_250:
	s_cmp_gt_u32 s16, 29
	s_cselect_b64 s[4:5], -1, 0
	s_and_b64 vcc, exec, s[4:5]
	s_cbranch_vccnz .LBB0_252
	s_mul_i32 s6, s13, 0x6000
	s_add_i32 s6, s18, s6
	v_lshl_add_u64 v[146:147], s[0:1], 1, v[140:141]
	s_mov_b32 m0, s6
	s_nop 0
	global_load_lds_dwordx4 v[146:147], off
	v_lshl_add_u64 v[146:147], s[0:1], 1, v[138:139]
	s_add_i32 m0, s6, 0x1000
	s_nop 0
	global_load_lds_dwordx4 v[146:147], off
	v_lshl_add_u64 v[146:147], s[0:1], 1, v[136:137]
	s_add_i32 m0, s6, 0x2000
	s_nop 0
	global_load_lds_dwordx4 v[146:147], off
	v_lshl_add_u64 v[146:147], s[0:1], 1, v[134:135]
	s_add_i32 m0, s6, 0x3000
	s_nop 0
	global_load_lds_dwordx4 v[146:147], off
	v_lshl_add_u64 v[146:147], v[132:133], 0, s[0:1]
	s_add_i32 m0, s6, 0x4000
	s_nop 0
	global_load_lds_dwordx4 v[146:147], off
	v_lshl_add_u64 v[146:147], v[130:131], 0, s[0:1]
	s_add_i32 m0, s6, 0x5000
	s_nop 0
	global_load_lds_dwordx4 v[146:147], off

; DI int otid() { int t = threadIdx.x; asm volatile("" : "+v"(t)); return t; }
;   DI bf16* K() const { return (bf16*)(p.ws + WS_K); }
; template <class AP, class BP, class Epi>
; DI void mfma_gemm_big_tile(const AP& aptr, const BP& bptr, int m0, int n0, int K, const Epi& epi, bf16* lds) {
;   const int tid = otid(), lane = tid & 63, wave = __builtin_amdgcn_readfirstlane(tid >> 6);
;   const int wm = (wave >> 1) * 128, wn = (wave & 1) * 64;
;   const int l16 = lane & 15, lq = lane >> 4;
;   const int lrow = tid >> 2, lcol = ((tid & 3) ^ ((-(tid >> 4)) & 3)) * 8;
;   const bf16* ap[4]; const bf16* bp[2];
; #pragma unroll
;   for (int i = 0; i < 4; ++i) ap[i] = aptr(m0 + lrow + 64 * i) + lcol;
; #pragma unroll
;   for (int i = 0; i < 2; ++i) bp[i] = bptr(n0 + lrow + 64 * i) + lcol;
;   f32x4 acc[8][4];
; #pragma unroll
;   for (int i = 0; i < 8; ++i)
; #pragma unroll
;     for (int j = 0; j < 4; ++j) acc[i][j] = f32x4{0.f, 0.f, 0.f, 0.f};
;   const int nk = K >> 5;
;     ...
;   BG_ISSUE(0, 0);
;   BG_ISSUE(1, 1);
; template <class AP, class BP, class Epi>
; DI void mfma_gemm_big(const AP& aptr, const BP& bptr, int M, int N, int K, const Epi& epi, bf16* lds) {
;   const int tn = N / 128, tiles = (M / 256) * tn;
;   xcd_items(tiles, [&](int t) { mfma_gemm_big_tile(aptr, bptr, (t / tn) * 256, (t % tn) * 128, K, epi, lds); });
.LBB0_508:
	s_mul_i32 s0, s8, s2
	s_add_i32 s0, s9, s0
	s_mul_hi_i32 s1, s0, 0x66666667
	s_lshr_b32 s4, s1, 31
	s_ashr_i32 s1, s1, 3
	v_mov_b32_e32 v26, v172
	s_add_i32 s1, s1, s4
	s_lshl_b32 s10, s1, 8
	v_lshrrev_b32_e32 v142, 4, v26
	s_mul_i32 s1, s1, 20
	v_sub_u32_e32 v27, 0, v142
	s_sub_i32 s0, s0, s1
	v_ashrrev_i32_e32 v18, 2, v26
	v_xor_b32_e32 v0, v26, v27
	s_lshl_b32 s11, s0, 7
	v_readfirstlane_b32 s0, v26
	v_add_u32_e32 v2, s10, v18
	v_lshlrev_b32_e32 v0, 4, v0
	s_and_b32 s12, s0, 64
	v_and_b32_e32 v0, 48, v0
	v_ashrrev_i32_e32 v3, 31, v2
	v_add_u32_e32 v10, 64, v2
	s_and_b32 s16, s0, 0xffffff80
	s_lshl_b32 s0, s0, 4
	v_lshl_add_u64 v[4:5], s[60:61], 0, v[0:1]
	v_bfe_u32 v30, v26, 2, 1
	v_mul_i32_i24_e32 v30, 0xfffff840, v30
	v_ashrrev_i32_e32 v31, 31, v30
	v_lshl_add_u64 v[4:5], v[4:5], 0, v[30:31]
	v_lshlrev_b64 v[6:7], 11, v[2:3]
	v_ashrrev_i32_e32 v11, 31, v10
	v_add_u32_e32 v14, 0x80, v2
	s_and_b32 s17, s0, 0xfffffc00
	v_lshl_add_u64 v[8:9], v[4:5], 0, v[6:7]
	v_lshlrev_b64 v[10:11], 11, v[10:11]
	v_ashrrev_i32_e32 v15, 31, v14
	v_add_u32_e32 v2, 0xc0, v2
	v_add_u32_e32 v18, s11, v18
	s_mov_b32 m0, s17
	v_lshl_add_u64 v[12:13], v[4:5], 0, v[10:11]
	v_lshlrev_b64 v[14:15], 11, v[14:15]
	v_ashrrev_i32_e32 v3, 31, v2
	v_ashrrev_i32_e32 v19, 31, v18
	global_load_lds_dwordx4 v[8:9], off
	s_add_i32 m0, s17, 0x1000
	v_lshl_add_u64 v[16:17], v[4:5], 0, v[14:15]
	v_lshlrev_b64 v[2:3], 11, v[2:3]
	v_lshlrev_b64 v[22:23], 11, v[18:19]
	v_add_u32_e32 v18, 64, v18
	global_load_lds_dwordx4 v[12:13], off
	s_add_i32 m0, s17, 0x2000
	v_lshl_add_u64 v[4:5], v[4:5], 0, v[2:3]
	v_lshl_add_u64 v[20:21], s[52:53], 0, v[0:1]
	v_ashrrev_i32_e32 v19, 31, v18
	global_load_lds_dwordx4 v[16:17], off
	s_add_i32 m0, s17, 0x3000
	v_lshl_add_u64 v[24:25], v[20:21], 0, v[22:23]
	v_lshlrev_b64 v[18:19], 11, v[18:19]
	global_load_lds_dwordx4 v[4:5], off
	s_add_i32 m0, s17, 0x4000
	v_lshl_add_u64 v[20:21], v[20:21], 0, v[18:19]
	global_load_lds_dwordx4 v[24:25], off
	s_add_i32 m0, s17, 0x5000
	v_lshl_add_u64 v[8:9], v[8:9], 0, 64
	v_lshl_add_u64 v[8:9], v[8:9], 0, 64
	global_load_lds_dwordx4 v[20:21], off
	s_add_i32 m0, s17, 0x6000
	v_lshl_add_u64 v[4:5], v[4:5], 0, 64
	v_lshl_add_u64 v[4:5], v[4:5], 0, 64
	global_load_lds_dwordx4 v[8:9], off
	v_lshl_add_u64 v[8:9], v[12:13], 0, 64
	v_lshl_add_u64 v[8:9], v[8:9], 0, 64
	s_add_i32 m0, s17, 0x7000
	v_and_b32_e32 v0, 15, v26
	global_load_lds_dwordx4 v[8:9], off
	v_lshl_add_u64 v[8:9], v[16:17], 0, 64
	v_lshl_add_u64 v[8:9], v[8:9], 0, 64
	s_add_i32 m0, s17, 0x8000
	v_readlane_b32 s0, v253, 53
	global_load_lds_dwordx4 v[8:9], off
	s_add_i32 m0, s17, 0x9000
	v_readlane_b32 s1, v253, 54
	global_load_lds_dwordx4 v[4:5], off
	v_lshl_add_u64 v[4:5], v[24:25], 0, 64
	s_add_i32 m0, s17, 0xa000
	s_mov_b32 s13, 2
	global_load_lds_dwordx4 v[4:5], off
	v_lshl_add_u64 v[4:5], v[20:21], 0, 64
	s_add_i32 m0, s17, 0xb000
	s_mov_b32 s15, 0
	global_load_lds_dwordx4 v[4:5], off
	v_lshrrev_b32_e32 v5, 2, v26
	v_sub_u32_e32 v5, 0, v5
	v_xor_b32_e32 v5, v142, v5
	v_lshlrev_b32_e32 v5, 4, v5
	v_or_b32_e32 v4, s16, v0
	v_and_b32_e32 v5, 48, v5
	v_lshl_or_b32 v143, v4, 6, v5
	v_or_b32_e32 v4, s12, v0
	v_lshlrev_b32_e32 v4, 6, v4
	v_or3_b32 v144, v5, v4, s77
	v_bitop3_b32 v4, v26, 3, v27 bitop3:0x48
	v_lshlrev_b32_e32 v4, 4, v4
	v_or_b32_e32 v18, v18, v4
	v_or_b32_e32 v22, v22, v4
	v_lshl_add_u64 v[130:131], s[0:1], 0, v[18:19]
	v_lshl_add_u64 v[132:133], s[0:1], 0, v[22:23]
	v_readlane_b32 s0, v253, 55
	s_waitcnt vmcnt(6)
	s_barrier
;   DI bf16* K() const { return (bf16*)(p.ws + WS_K); }
; template <class AP, class BP, class Epi>
; DI void mfma_gemm_big_tile(const AP& aptr, const BP& bptr, int m0, int n0, int K, const Epi& epi, bf16* lds) {
;     ...
;   const bf16* ap[4]; const bf16* bp[2];
; #pragma unroll
;   for (int i = 0; i < 4; ++i) ap[i] = aptr(m0 + lrow + 64 * i) + lcol;
; #pragma unroll
;   for (int i = 0; i < 2; ++i) bp[i] = bptr(n0 + lrow + 64 * i) + lcol;
;   f32x4 acc[8][4];
; #pragma unroll
;   for (int i = 0; i < 8; ++i)
; #pragma unroll
;     for (int j = 0; j < 4; ++j) acc[i][j] = f32x4{0.f, 0.f, 0.f, 0.f};
;   const int nk = K >> 5;
	v_or_b32_e32 v2, v2, v4
	v_readlane_b32 s1, v253, 56
	v_or_b32_e32 v14, v14, v4
	v_or_b32_e32 v10, v10, v4
	v_lshl_add_u64 v[134:135], s[0:1], 0, v[2:3]
	v_or_b32_e32 v6, v6, v4
	v_mov_b32_e32 v2, 0
	v_lshl_add_u64 v[136:137], s[0:1], 0, v[14:15]
	v_lshl_add_u64 v[138:139], s[0:1], 0, v[10:11]
	v_lshl_add_u64 v[140:141], s[0:1], 0, v[6:7]
	v_lshl_add_u64 v[30:31], v[30:31], 0, 64
	v_lshl_add_u64 v[30:31], v[30:31], 0, 64
	v_lshl_add_u64 v[134:135], v[134:135], 0, v[30:31]
	v_lshl_add_u64 v[136:137], v[136:137], 0, v[30:31]
	v_lshl_add_u64 v[138:139], v[138:139], 0, v[30:31]
	v_lshl_add_u64 v[140:141], v[140:141], 0, v[30:31]
	s_mov_b64 s[0:1], 0
	s_mov_b32 s18, 0
	v_mov_b32_e32 v3, v2
	v_mov_b32_e32 v4, v2
	v_mov_b32_e32 v5, v2
	v_mov_b32_e32 v6, v2
	v_mov_b32_e32 v7, v2
	v_mov_b32_e32 v8, v2
	v_mov_b32_e32 v9, v2
	v_mov_b32_e32 v10, v2
	v_mov_b32_e32 v11, v2
	v_mov_b32_e32 v12, v2
	v_mov_b32_e32 v13, v2
	v_mov_b32_e32 v14, v2
	v_mov_b32_e32 v15, v2
	v_mov_b32_e32 v16, v2
	v_mov_b32_e32 v17, v2
	v_mov_b32_e32 v18, v2
	v_mov_b32_e32 v19, v2
	v_mov_b32_e32 v20, v2
	v_mov_b32_e32 v21, v2
	v_mov_b32_e32 v22, v2
	v_mov_b32_e32 v23, v2
	v_mov_b32_e32 v24, v2
	v_mov_b32_e32 v25, v2
	v_mov_b32_e32 v26, v2
	v_mov_b32_e32 v27, v2
	v_mov_b32_e32 v28, v2
	v_mov_b32_e32 v29, v2
	v_mov_b32_e32 v30, v2
	v_mov_b32_e32 v31, v2
	v_mov_b32_e32 v32, v2
	v_mov_b32_e32 v33, v2
	v_mov_b32_e32 v34, v2
	v_mov_b32_e32 v35, v2
	v_mov_b32_e32 v36, v2
	v_mov_b32_e32 v37, v2
	v_mov_b32_e32 v38, v2
	v_mov_b32_e32 v39, v2
	v_mov_b32_e32 v40, v2
	v_mov_b32_e32 v41, v2
	v_mov_b32_e32 v42, v2
	v_mov_b32_e32 v43, v2
	v_mov_b32_e32 v44, v2
	v_mov_b32_e32 v45, v2
	v_mov_b32_e32 v46, v2
	v_mov_b32_e32 v47, v2
	v_mov_b32_e32 v48, v2
	v_mov_b32_e32 v49, v2
	v_mov_b32_e32 v50, v2
	v_mov_b32_e32 v51, v2
	v_mov_b32_e32 v52, v2
	v_mov_b32_e32 v53, v2
	v_mov_b32_e32 v54, v2
	v_mov_b32_e32 v55, v2
	v_mov_b32_e32 v56, v2
	v_mov_b32_e32 v57, v2
	v_mov_b32_e32 v58, v2
	v_mov_b32_e32 v59, v2
	v_mov_b32_e32 v60, v2
	v_mov_b32_e32 v61, v2
	v_mov_b32_e32 v62, v2
	v_mov_b32_e32 v63, v2
	v_mov_b32_e32 v64, v2
	v_mov_b32_e32 v65, v2
	v_mov_b32_e32 v66, v2
	v_mov_b32_e32 v67, v2
	v_mov_b32_e32 v68, v2
	v_mov_b32_e32 v69, v2
	v_mov_b32_e32 v70, v2
	v_mov_b32_e32 v71, v2
	v_mov_b32_e32 v72, v2
	v_mov_b32_e32 v73, v2
	v_mov_b32_e32 v74, v2
	v_mov_b32_e32 v75, v2
	v_mov_b32_e32 v76, v2
	v_mov_b32_e32 v77, v2
	v_mov_b32_e32 v78, v2
	v_mov_b32_e32 v79, v2
	v_mov_b32_e32 v80, v2
	v_mov_b32_e32 v81, v2
	v_mov_b32_e32 v82, v2
	v_mov_b32_e32 v83, v2
	v_mov_b32_e32 v84, v2
	v_mov_b32_e32 v85, v2
	v_mov_b32_e32 v86, v2
	v_mov_b32_e32 v87, v2
	v_mov_b32_e32 v88, v2
	v_mov_b32_e32 v89, v2
	v_mov_b32_e32 v90, v2
	v_mov_b32_e32 v91, v2
	v_mov_b32_e32 v92, v2
	v_mov_b32_e32 v93, v2
	v_mov_b32_e32 v94, v2
	v_mov_b32_e32 v95, v2
	v_mov_b32_e32 v96, v2
	v_mov_b32_e32 v97, v2
	v_mov_b32_e32 v98, v2
	v_mov_b32_e32 v99, v2
	v_mov_b32_e32 v100, v2
	v_mov_b32_e32 v101, v2
	v_mov_b32_e32 v102, v2
	v_mov_b32_e32 v103, v2
	v_mov_b32_e32 v104, v2
	v_mov_b32_e32 v105, v2
	v_mov_b32_e32 v106, v2
	v_mov_b32_e32 v107, v2
	v_mov_b32_e32 v108, v2
	v_mov_b32_e32 v109, v2
	v_mov_b32_e32 v110, v2
	v_mov_b32_e32 v111, v2
	v_mov_b32_e32 v112, v2
	v_mov_b32_e32 v113, v2
	v_mov_b32_e32 v114, v2
	v_mov_b32_e32 v115, v2
	v_mov_b32_e32 v116, v2
	v_mov_b32_e32 v117, v2
	v_mov_b32_e32 v118, v2
	v_mov_b32_e32 v119, v2
	v_mov_b32_e32 v120, v2
	v_mov_b32_e32 v121, v2
	v_mov_b32_e32 v122, v2
	v_mov_b32_e32 v123, v2
	v_mov_b32_e32 v124, v2
	v_mov_b32_e32 v125, v2
	v_mov_b32_e32 v126, v2
	v_mov_b32_e32 v127, v2
	v_mov_b32_e32 v128, v2
	v_mov_b32_e32 v129, v2
	s_branch .LBB0_510

; template <class AP, class BP, class Epi>
; DI void mfma_gemm_big_tile(const AP& aptr, const BP& bptr, int m0, int n0, int K, const Epi& epi, bf16* lds) {
;     ...
;   BG_ISSUE(0, 0);
;   BG_ISSUE(1, 1);
;   asm volatile("s_waitcnt vmcnt(6)\n\ts_barrier" ::: "memory");
;   const unsigned lbase = (unsigned)(size_t)lds;
;   const unsigned a_off = (unsigned)(((wm + l16) * 32 + (lq ^ ((-(l16 >> 2)) & 3)) * 8) * 2);
;   const unsigned b_off = (unsigned)((256 * 32 + (wn + l16) * 32 + (lq ^ ((-(l16 >> 2)) & 3)) * 8) * 2);
;     ...
;   int cur = 0, nxt = 2;
;   for (int ks = 0; ks < nk; ++ks) {
;     if (ks + 2 < nk) BG_ISSUE(nxt, ks + 2);
.LBB0_510:
	s_cmp_gt_u32 s15, 29
	s_cselect_b64 s[4:5], -1, 0
	s_and_b64 vcc, exec, s[4:5]
	s_cbranch_vccnz .LBB0_512
	s_mul_i32 s6, s13, 0x6000
	s_add_i32 s6, s17, s6
	v_lshl_add_u64 v[146:147], s[0:1], 1, v[140:141]
	s_mov_b32 m0, s6
	s_nop 0
	global_load_lds_dwordx4 v[146:147], off
	v_lshl_add_u64 v[146:147], s[0:1], 1, v[138:139]
	s_add_i32 m0, s6, 0x1000
	s_nop 0
	global_load_lds_dwordx4 v[146:147], off
	v_lshl_add_u64 v[146:147], s[0:1], 1, v[136:137]
	s_add_i32 m0, s6, 0x2000
	s_nop 0
	global_load_lds_dwordx4 v[146:147], off
	v_lshl_add_u64 v[146:147], s[0:1], 1, v[134:135]
	s_add_i32 m0, s6, 0x3000
	s_nop 0
	global_load_lds_dwordx4 v[146:147], off
	v_lshl_add_u64 v[146:147], v[132:133], 0, s[0:1]
	s_add_i32 m0, s6, 0x4000
	s_nop 0
	global_load_lds_dwordx4 v[146:147], off
	v_lshl_add_u64 v[146:147], v[130:131], 0, s[0:1]
	s_add_i32 m0, s6, 0x5000
	s_nop 0
	global_load_lds_dwordx4 v[146:147], off

; DI int otid() { int t = threadIdx.x; asm volatile("" : "+v"(t)); return t; }
;   DI float* xrow(int row) const { return row < MLAT ? p.out + (size_t)row * D : XC() + (size_t)(row - MLAT) * D; }
; DI void ln_row(const Ctx& c, int row, int l_post, int l_next, int lane) {
;   const Params& p = c.p;
;     const bool lat = row < MLAT;
;     const bool do_post = (l_post >= 0) && (lat || l_post <= 1);
;     const bool do_h = (l_next >= 0) && (lat || l_next <= 2);
;     if (!do_post && !do_h) return;
;     if (l_post >= 0 && !do_post) return;
;     const float* src = (l_post < 0) ? c.xin(row) : c.xrow(row);
; DI void phase_ln(const Ctx& c, int l_post, int l_next) {
;   const int tid = otid(), lane = tid & 63;
;   const int wv = (blockIdx.x * NT + tid) >> 6, nw = (gridDim.x * NT) >> 6;
;   for (int row = wv; row < MT; row += 2 * nw) { ln_row(c, row, l_post, l_next, lane); if (row + nw < MT) ln_row(c, row + nw, l_post, l_next, lane); }
.Llnl_entry:
	v_readlane_b32 s0, v252, 32
	v_lshrrev_b32_e32 v2, 6, v172
	s_nop 0
	v_readfirstlane_b32 s1, v2
	s_lshr_b32 s0, s0, 8
	s_and_b32 s15, s0, 7
	s_lshr_b32 s0, s0, 3
	s_lshl_b32 s0, s0, 2
	s_add_i32 s1, s0, s1
	s_lshl_b32 s10, s15, 11
	s_add_i32 s10, s10, s1
	s_lshl_b32 s15, s15, 6
	s_add_i32 s15, s15, s1
	s_addk_i32 s15, 0x4000
	s_cmp_lt_u32 s1, 64
	s_cselect_b32 s15, s15, 0
	s_cmp_lt_u32 s86, 2
	s_cselect_b32 s15, s15, 0
	s_mov_b32 s13, 0
	v_mbcnt_lo_u32_b32 v2, -1, 0
	v_mbcnt_hi_u32_b32 v2, -1, v2
	v_xor_b32_e32 v5, 16, v2
	v_lshlrev_b32_e32 v5, 2, v5
	v_lshrrev_b32_e32 v14, 3, v2
	v_lshlrev_b32_e32 v14, 7, v14
	v_and_b32_e32 v6, 7, v2
	v_lshl_or_b32 v14, v6, 3, v14
	v_lshlrev_b32_e32 v2, 4, v2
	s_cmp_lt_u32 s10, 0x4000
	s_cbranch_scc1 .Llnl_go
	s_cmp_lt_u32 s86, 2
	s_cbranch_scc0 .Llnl_exit

; DI int otid() { int t = threadIdx.x; asm volatile("" : "+v"(t)); return t; }
; DI void phase_ln(const Ctx& c, int l_post, int l_next) {
;   const int tid = otid(), lane = tid & 63;
;   const int wv = (blockIdx.x * NT + tid) >> 6, nw = (gridDim.x * NT) >> 6;
;   for (int row = wv; row < MT; row += 2 * nw) { ln_row(c, row, l_post, l_next, lane); if (row + nw < MT) ln_row(c, row + nw, l_post, l_next, lane); }
.Llnl_loop:
	s_add_u32 s13, s13, 1
	s_cmp_lt_u32 s13, 8
	s_cbranch_scc0 .Llnl_chk9A
	s_add_u32 s12, s10, 0x100
	s_branch .Llnl_preA
.Llnl_chk9A:
	s_cmp_eq_u32 s13, 8
	s_cbranch_scc0 .Llnl_lastA
	s_cmp_eq_u32 s15, 0
	s_cbranch_scc1 .Llnl_lastA
	s_mov_b32 s12, s15

;   DI float* xrow(int row) const { return row < MLAT ? p.out + (size_t)row * D : XC() + (size_t)(row - MLAT) * D; }
; DI void ln_row(const Ctx& c, int row, int l_post, int l_next, int lane) {
;     ...
;     if (do_post) {
;       float s = 0.f;
; #pragma unroll
;       for (int i = 0; i < 16; ++i) s += v[i];
;       const float mean = wave_sum(s) * (1.f / D);
;       float q = 0.f;
; #pragma unroll
;       for (int i = 0; i < 16; ++i) { v[i] -= mean; q += v[i] * v[i]; }
;       const float rstd = rsqrtf(wave_sum(q) * (1.f / D) + LN_EPS);
;       float* dst = c.xrow(row);
; #pragma unroll
;       for (int i = 0; i < 4; ++i) {
;         const int col = i * 256 + lane * 4;
;         const float4 g = *(const float4*)(p.post_g + l_post * D + col), b = *(const float4*)(p.post_b + l_post * D + col);
;         v[i * 4] = v[i * 4] * rstd * g.x + b.x; v[i * 4 + 1] = v[i * 4 + 1] * rstd * g.y + b.y;
;         v[i * 4 + 2] = v[i * 4 + 2] * rstd * g.z + b.z; v[i * 4 + 3] = v[i * 4 + 3] * rstd * g.w + b.w;
;         *(float4*)(dst + col) = make_float4(v[i * 4], v[i * 4 + 1], v[i * 4 + 2], v[i * 4 + 3]);
;       }
;     }
.Llnl_pjA:
	v_add_f32_e32 v6, v52, v53
	v_add_f32_e32 v6, v6, v54
	v_add_f32_e32 v6, v6, v55
	v_add_f32_e32 v6, v6, v56
	v_add_f32_e32 v6, v6, v57
	v_add_f32_e32 v6, v6, v58
	v_add_f32_e32 v6, v6, v59
	v_add_f32_e32 v6, v6, v60
	v_add_f32_e32 v6, v6, v61
	v_add_f32_e32 v6, v6, v62
	v_add_f32_e32 v6, v6, v63
	v_add_f32_e32 v6, v6, v64
	v_add_f32_e32 v6, v6, v65
	v_add_f32_e32 v6, v6, v66
	v_add_f32_e32 v6, v6, v67
	s_nop 1
	v_add_f32_dpp v6, v6, v6 row_ror:8 row_mask:0xf bank_mask:0xf bound_ctrl:1
	s_nop 1
	v_add_f32_dpp v6, v6, v6 row_ror:4 row_mask:0xf bank_mask:0xf bound_ctrl:1
	s_nop 1
	v_add_f32_dpp v6, v6, v6 row_ror:2 row_mask:0xf bank_mask:0xf bound_ctrl:1
	s_nop 1
	v_add_f32_dpp v6, v6, v6 row_ror:1 row_mask:0xf bank_mask:0xf bound_ctrl:1
	ds_bpermute_b32 v8, v5, v6
	s_waitcnt lgkmcnt(0)
	v_add_f32_e32 v6, v6, v8
	v_mov_b32_e32 v8, v6
	s_nop 1
	v_permlane32_swap_b32_e32 v6, v8
	v_add_f32_e32 v6, v6, v8
	v_mul_f32_e32 v6, 0x3a800000, v6
	v_sub_f32_e32 v52, v52, v6
	v_sub_f32_e32 v53, v53, v6
	v_sub_f32_e32 v54, v54, v6
	v_sub_f32_e32 v55, v55, v6
	v_sub_f32_e32 v56, v56, v6
	v_sub_f32_e32 v57, v57, v6
	v_sub_f32_e32 v58, v58, v6
	v_sub_f32_e32 v59, v59, v6
	v_sub_f32_e32 v60, v60, v6
	v_sub_f32_e32 v61, v61, v6
	v_sub_f32_e32 v62, v62, v6
	v_sub_f32_e32 v63, v63, v6
	v_sub_f32_e32 v64, v64, v6
	v_sub_f32_e32 v65, v65, v6
	v_sub_f32_e32 v66, v66, v6
	v_sub_f32_e32 v67, v67, v6
	v_mul_f32_e32 v7, v52, v52
	v_fmac_f32_e32 v7, v53, v53
	v_fmac_f32_e32 v7, v54, v54
	v_fmac_f32_e32 v7, v55, v55
	v_fmac_f32_e32 v7, v56, v56
	v_fmac_f32_e32 v7, v57, v57
	v_fmac_f32_e32 v7, v58, v58
	v_fmac_f32_e32 v7, v59, v59
	v_fmac_f32_e32 v7, v60, v60
	v_fmac_f32_e32 v7, v61, v61
	v_fmac_f32_e32 v7, v62, v62
	v_fmac_f32_e32 v7, v63, v63
	v_fmac_f32_e32 v7, v64, v64
	v_fmac_f32_e32 v7, v65, v65
	v_fmac_f32_e32 v7, v66, v66
	v_fmac_f32_e32 v7, v67, v67
	s_nop 1
	v_add_f32_dpp v7, v7, v7 row_ror:8 row_mask:0xf bank_mask:0xf bound_ctrl:1
	s_nop 1
	v_add_f32_dpp v7, v7, v7 row_ror:4 row_mask:0xf bank_mask:0xf bound_ctrl:1
	s_nop 1
	v_add_f32_dpp v7, v7, v7 row_ror:2 row_mask:0xf bank_mask:0xf bound_ctrl:1
	s_nop 1
	v_add_f32_dpp v7, v7, v7 row_ror:1 row_mask:0xf bank_mask:0xf bound_ctrl:1
	ds_bpermute_b32 v8, v5, v7
	s_waitcnt lgkmcnt(0)
	v_add_f32_e32 v7, v7, v8
	v_mov_b32_e32 v8, v7
	s_nop 1
	v_permlane32_swap_b32_e32 v7, v8
	v_add_f32_e32 v7, v7, v8
	v_mov_b32_e32 v8, 0x358637bd
	v_fmac_f32_e32 v8, 0x3a800000, v7
	v_rsq_f32_e32 v7, v8
	s_nop 0
	v_mul_f32_e32 v52, v52, v7
	v_mul_f32_e32 v53, v53, v7
	v_mul_f32_e32 v54, v54, v7
	v_mul_f32_e32 v55, v55, v7
	v_mul_f32_e32 v56, v56, v7
	v_mul_f32_e32 v57, v57, v7
	v_mul_f32_e32 v58, v58, v7
	v_mul_f32_e32 v59, v59, v7
	v_mul_f32_e32 v60, v60, v7
	v_mul_f32_e32 v61, v61, v7
	v_mul_f32_e32 v62, v62, v7
	v_mul_f32_e32 v63, v63, v7
	v_mul_f32_e32 v64, v64, v7
	v_mul_f32_e32 v65, v65, v7
	v_mul_f32_e32 v66, v66, v7
	v_mul_f32_e32 v67, v67, v7
	v_fma_f32 v52, v52, v20, v36
	v_fma_f32 v53, v53, v21, v37
	v_fma_f32 v54, v54, v22, v38
	v_fma_f32 v55, v55, v23, v39
	v_fma_f32 v56, v56, v24, v40
	v_fma_f32 v57, v57, v25, v41
	v_fma_f32 v58, v58, v26, v42
	v_fma_f32 v59, v59, v27, v43
	v_fma_f32 v60, v60, v28, v44
	v_fma_f32 v61, v61, v29, v45
	v_fma_f32 v62, v62, v30, v46
	v_fma_f32 v63, v63, v31, v47
	v_fma_f32 v64, v64, v32, v48
	v_fma_f32 v65, v65, v33, v49
	v_fma_f32 v66, v66, v34, v50
	v_fma_f32 v67, v67, v35, v51
	global_store_dwordx4 v2, v[52:55], s[26:27] offset:0
	global_store_dwordx4 v2, v[56:59], s[26:27] offset:1024
	global_store_dwordx4 v2, v[60:63], s[26:27] offset:2048
	global_store_dwordx4 v2, v[64:67], s[26:27] offset:3072
	s_cmp_lt_u32 s86, 3
	s_cbranch_scc0 .Llnl_nohA
; DI bf16 f2bf(float f) { unsigned u = __float_as_uint(f); u += 0x7fffu + ((u >> 16) & 1u); return (bf16)(u >> 16); }
;   DI float* MOD() const { return (float*)(p.ws + WS_MOD); }
;   DI bf16* HY() const { return (bf16*)(p.ws + WS_HY); }
; DI void ln_row(const Ctx& c, int row, int l_post, int l_next, int lane) {
;     ...
;     if (do_h) {
;       float s = 0.f;
; #pragma unroll
;       for (int i = 0; i < 16; ++i) s += v[i];
;       const float mean = wave_sum(s) * (1.f / D);
;       float q = 0.f;
; #pragma unroll
;       for (int i = 0; i < 16; ++i) { v[i] -= mean; q += v[i] * v[i]; }
;       const float rstd = rsqrtf(wave_sum(q) * (1.f / D) + LN_EPS);
;       const float* md = c.MOD() + (l_next * 3 + mod_row(row)) * 3072;
;       bf16* dst = c.HY() + (size_t)row * D;
; #pragma unroll
;       for (int i = 0; i < 4; ++i) {
;         const int col = i * 256 + lane * 4;
;         const float4 sh = *(const float4*)(md + col), sc = *(const float4*)(md + 1024 + col);
;         const float h0 = v[i * 4] * rstd * (1.f + sc.x) + sh.x, h1 = v[i * 4 + 1] * rstd * (1.f + sc.y) + sh.y;
;         const float h2 = v[i * 4 + 2] * rstd * (1.f + sc.z) + sh.z, h3 = v[i * 4 + 3] * rstd * (1.f + sc.w) + sh.w;
;         uint2 pk; pk.x = (unsigned)f2bf(h0) | ((unsigned)f2bf(h1) << 16); pk.y = (unsigned)f2bf(h2) | ((unsigned)f2bf(h3) << 16);
;         *(uint2*)(dst + col) = pk;
;       }
	s_lshr_b32 s26, s10, 1
	s_lshl_b32 s26, s26, 12
	s_and_b32 s2, s10, 1
	s_lshl_b32 s2, s2, 6
	s_or_b32 s26, s26, s2
	s_add_u32 s26, s88, s26
	s_addc_u32 s27, s89, 0
	s_add_u32 s26, s26, 0x1128000
	s_addc_u32 s27, s27, 0
	v_add_f32_e32 v6, v52, v53
	v_add_f32_e32 v6, v6, v54
	v_add_f32_e32 v6, v6, v55
	v_add_f32_e32 v6, v6, v56
	v_add_f32_e32 v6, v6, v57
	v_add_f32_e32 v6, v6, v58
	v_add_f32_e32 v6, v6, v59
	v_add_f32_e32 v6, v6, v60
	v_add_f32_e32 v6, v6, v61
	v_add_f32_e32 v6, v6, v62
	v_add_f32_e32 v6, v6, v63
	v_add_f32_e32 v6, v6, v64
	v_add_f32_e32 v6, v6, v65
	v_add_f32_e32 v6, v6, v66
	v_add_f32_e32 v6, v6, v67
	s_nop 1
	v_add_f32_dpp v6, v6, v6 row_ror:8 row_mask:0xf bank_mask:0xf bound_ctrl:1
	s_nop 1
	v_add_f32_dpp v6, v6, v6 row_ror:4 row_mask:0xf bank_mask:0xf bound_ctrl:1
	s_nop 1
	v_add_f32_dpp v6, v6, v6 row_ror:2 row_mask:0xf bank_mask:0xf bound_ctrl:1
	s_nop 1
	v_add_f32_dpp v6, v6, v6 row_ror:1 row_mask:0xf bank_mask:0xf bound_ctrl:1
	ds_bpermute_b32 v8, v5, v6
	s_waitcnt lgkmcnt(0)
	v_add_f32_e32 v6, v6, v8
	v_mov_b32_e32 v8, v6
	s_nop 1
	v_permlane32_swap_b32_e32 v6, v8
	v_add_f32_e32 v6, v6, v8
	v_mul_f32_e32 v6, 0x3a800000, v6
	v_sub_f32_e32 v52, v52, v6
	v_sub_f32_e32 v53, v53, v6
	v_sub_f32_e32 v54, v54, v6
	v_sub_f32_e32 v55, v55, v6
	v_sub_f32_e32 v56, v56, v6
	v_sub_f32_e32 v57, v57, v6
	v_sub_f32_e32 v58, v58, v6
	v_sub_f32_e32 v59, v59, v6
	v_sub_f32_e32 v60, v60, v6
	v_sub_f32_e32 v61, v61, v6
	v_sub_f32_e32 v62, v62, v6
	v_sub_f32_e32 v63, v63, v6
	v_sub_f32_e32 v64, v64, v6
	v_sub_f32_e32 v65, v65, v6
	v_sub_f32_e32 v66, v66, v6
	v_sub_f32_e32 v67, v67, v6
	v_mul_f32_e32 v7, v52, v52
	v_fmac_f32_e32 v7, v53, v53
	v_fmac_f32_e32 v7, v54, v54
	v_fmac_f32_e32 v7, v55, v55
	v_fmac_f32_e32 v7, v56, v56
	v_fmac_f32_e32 v7, v57, v57
	v_fmac_f32_e32 v7, v58, v58
	v_fmac_f32_e32 v7, v59, v59
	v_fmac_f32_e32 v7, v60, v60
	v_fmac_f32_e32 v7, v61, v61
	v_fmac_f32_e32 v7, v62, v62
	v_fmac_f32_e32 v7, v63, v63
	v_fmac_f32_e32 v7, v64, v64
	v_fmac_f32_e32 v7, v65, v65
	v_fmac_f32_e32 v7, v66, v66
	v_fmac_f32_e32 v7, v67, v67
	s_nop 1
	v_add_f32_dpp v7, v7, v7 row_ror:8 row_mask:0xf bank_mask:0xf bound_ctrl:1
	s_nop 1
	v_add_f32_dpp v7, v7, v7 row_ror:4 row_mask:0xf bank_mask:0xf bound_ctrl:1
	s_nop 1
	v_add_f32_dpp v7, v7, v7 row_ror:2 row_mask:0xf bank_mask:0xf bound_ctrl:1
	s_nop 1
	v_add_f32_dpp v7, v7, v7 row_ror:1 row_mask:0xf bank_mask:0xf bound_ctrl:1
	ds_bpermute_b32 v8, v5, v7
	s_waitcnt lgkmcnt(0)
	v_add_f32_e32 v7, v7, v8
	v_mov_b32_e32 v8, v7
	s_nop 1
	v_permlane32_swap_b32_e32 v7, v8
	v_add_f32_e32 v7, v7, v8
	v_mov_b32_e32 v8, 0x358637bd
	v_fmac_f32_e32 v8, 0x3a800000, v7
	v_rsq_f32_e32 v7, v8
	s_nop 0
	v_mul_f32_e32 v52, v52, v7
	v_mul_f32_e32 v53, v53, v7
	v_mul_f32_e32 v54, v54, v7
	v_mul_f32_e32 v55, v55, v7
	v_mul_f32_e32 v56, v56, v7
	v_mul_f32_e32 v57, v57, v7
	v_mul_f32_e32 v58, v58, v7
	v_mul_f32_e32 v59, v59, v7
	v_mul_f32_e32 v60, v60, v7
	v_mul_f32_e32 v61, v61, v7
	v_mul_f32_e32 v62, v62, v7
	v_mul_f32_e32 v63, v63, v7
	v_mul_f32_e32 v64, v64, v7
	v_mul_f32_e32 v65, v65, v7
	v_mul_f32_e32 v66, v66, v7
	v_mul_f32_e32 v67, v67, v7
	v_add_f32_e32 v100, 1.0, v100
	v_add_f32_e32 v101, 1.0, v101
	v_add_f32_e32 v102, 1.0, v102
	v_add_f32_e32 v103, 1.0, v103
	v_add_f32_e32 v104, 1.0, v104
	v_add_f32_e32 v105, 1.0, v105
	v_add_f32_e32 v106, 1.0, v106
	v_add_f32_e32 v107, 1.0, v107
	v_add_f32_e32 v108, 1.0, v108
	v_add_f32_e32 v109, 1.0, v109
	v_add_f32_e32 v110, 1.0, v110
	v_add_f32_e32 v111, 1.0, v111
	v_add_f32_e32 v112, 1.0, v112
	v_add_f32_e32 v113, 1.0, v113
	v_add_f32_e32 v114, 1.0, v114
	v_add_f32_e32 v115, 1.0, v115
	v_fma_f32 v52, v52, v100, v84
	v_fma_f32 v53, v53, v101, v85
	v_fma_f32 v54, v54, v102, v86
	v_fma_f32 v55, v55, v103, v87
	v_fma_f32 v56, v56, v104, v88
	v_fma_f32 v57, v57, v105, v89
	v_fma_f32 v58, v58, v106, v90
	v_fma_f32 v59, v59, v107, v91
	v_fma_f32 v60, v60, v108, v92
	v_fma_f32 v61, v61, v109, v93
	v_fma_f32 v62, v62, v110, v94
	v_fma_f32 v63, v63, v111, v95
	v_fma_f32 v64, v64, v112, v96
	v_fma_f32 v65, v65, v113, v97
	v_fma_f32 v66, v66, v114, v98
	v_fma_f32 v67, v67, v115, v99
	v_cvt_pk_bf16_f32 v52, v52, v53
	v_cvt_pk_bf16_f32 v53, v54, v55
	v_cvt_pk_bf16_f32 v54, v56, v57
	v_cvt_pk_bf16_f32 v55, v58, v59
	v_cvt_pk_bf16_f32 v56, v60, v61
	v_cvt_pk_bf16_f32 v57, v62, v63
	v_cvt_pk_bf16_f32 v58, v64, v65
	v_cvt_pk_bf16_f32 v59, v66, v67
	global_store_dwordx2 v14, v[52:53], s[26:27] offset:0
	global_store_dwordx2 v14, v[54:55], s[26:27] offset:1024
	global_store_dwordx2 v14, v[56:57], s[26:27] offset:2048
	global_store_dwordx2 v14, v[58:59], s[26:27] offset:3072

;   DI float* xrow(int row) const { return row < MLAT ? p.out + (size_t)row * D : XC() + (size_t)(row - MLAT) * D; }
; DI void ln_row(const Ctx& c, int row, int l_post, int l_next, int lane) {
;     ...
;     if (do_post) {
;       float s = 0.f;
; #pragma unroll
;       for (int i = 0; i < 16; ++i) s += v[i];
;       const float mean = wave_sum(s) * (1.f / D);
;       float q = 0.f;
; #pragma unroll
;       for (int i = 0; i < 16; ++i) { v[i] -= mean; q += v[i] * v[i]; }
;       const float rstd = rsqrtf(wave_sum(q) * (1.f / D) + LN_EPS);
;       float* dst = c.xrow(row);
; #pragma unroll
;       for (int i = 0; i < 4; ++i) {
;         const int col = i * 256 + lane * 4;
;         const float4 g = *(const float4*)(p.post_g + l_post * D + col), b = *(const float4*)(p.post_b + l_post * D + col);
;         v[i * 4] = v[i * 4] * rstd * g.x + b.x; v[i * 4 + 1] = v[i * 4 + 1] * rstd * g.y + b.y;
;         v[i * 4 + 2] = v[i * 4 + 2] * rstd * g.z + b.z; v[i * 4 + 3] = v[i * 4 + 3] * rstd * g.w + b.w;
;         *(float4*)(dst + col) = make_float4(v[i * 4], v[i * 4 + 1], v[i * 4 + 2], v[i * 4 + 3]);
;       }
;     }
.Llnl_pjB:
	v_add_f32_e32 v6, v68, v69
	v_add_f32_e32 v6, v6, v70
	v_add_f32_e32 v6, v6, v71
	v_add_f32_e32 v6, v6, v72
	v_add_f32_e32 v6, v6, v73
	v_add_f32_e32 v6, v6, v74
	v_add_f32_e32 v6, v6, v75
	v_add_f32_e32 v6, v6, v76
	v_add_f32_e32 v6, v6, v77
	v_add_f32_e32 v6, v6, v78
	v_add_f32_e32 v6, v6, v79
	v_add_f32_e32 v6, v6, v80
	v_add_f32_e32 v6, v6, v81
	v_add_f32_e32 v6, v6, v82
	v_add_f32_e32 v6, v6, v83
	s_nop 1
	v_add_f32_dpp v6, v6, v6 row_ror:8 row_mask:0xf bank_mask:0xf bound_ctrl:1
	s_nop 1
	v_add_f32_dpp v6, v6, v6 row_ror:4 row_mask:0xf bank_mask:0xf bound_ctrl:1
	s_nop 1
	v_add_f32_dpp v6, v6, v6 row_ror:2 row_mask:0xf bank_mask:0xf bound_ctrl:1
	s_nop 1
	v_add_f32_dpp v6, v6, v6 row_ror:1 row_mask:0xf bank_mask:0xf bound_ctrl:1
	ds_bpermute_b32 v8, v5, v6
	s_waitcnt lgkmcnt(0)
	v_add_f32_e32 v6, v6, v8
	v_mov_b32_e32 v8, v6
	s_nop 1
	v_permlane32_swap_b32_e32 v6, v8
	v_add_f32_e32 v6, v6, v8
	v_mul_f32_e32 v6, 0x3a800000, v6
	v_sub_f32_e32 v68, v68, v6
	v_sub_f32_e32 v69, v69, v6
	v_sub_f32_e32 v70, v70, v6
	v_sub_f32_e32 v71, v71, v6
	v_sub_f32_e32 v72, v72, v6
	v_sub_f32_e32 v73, v73, v6
	v_sub_f32_e32 v74, v74, v6
	v_sub_f32_e32 v75, v75, v6
	v_sub_f32_e32 v76, v76, v6
	v_sub_f32_e32 v77, v77, v6
	v_sub_f32_e32 v78, v78, v6
	v_sub_f32_e32 v79, v79, v6
	v_sub_f32_e32 v80, v80, v6
	v_sub_f32_e32 v81, v81, v6
	v_sub_f32_e32 v82, v82, v6
	v_sub_f32_e32 v83, v83, v6
	v_mul_f32_e32 v7, v68, v68
	v_fmac_f32_e32 v7, v69, v69
	v_fmac_f32_e32 v7, v70, v70
	v_fmac_f32_e32 v7, v71, v71
	v_fmac_f32_e32 v7, v72, v72
	v_fmac_f32_e32 v7, v73, v73
	v_fmac_f32_e32 v7, v74, v74
	v_fmac_f32_e32 v7, v75, v75
	v_fmac_f32_e32 v7, v76, v76
	v_fmac_f32_e32 v7, v77, v77
	v_fmac_f32_e32 v7, v78, v78
	v_fmac_f32_e32 v7, v79, v79
	v_fmac_f32_e32 v7, v80, v80
	v_fmac_f32_e32 v7, v81, v81
	v_fmac_f32_e32 v7, v82, v82
	v_fmac_f32_e32 v7, v83, v83
	s_nop 1
	v_add_f32_dpp v7, v7, v7 row_ror:8 row_mask:0xf bank_mask:0xf bound_ctrl:1
	s_nop 1
	v_add_f32_dpp v7, v7, v7 row_ror:4 row_mask:0xf bank_mask:0xf bound_ctrl:1
	s_nop 1
	v_add_f32_dpp v7, v7, v7 row_ror:2 row_mask:0xf bank_mask:0xf bound_ctrl:1
	s_nop 1
	v_add_f32_dpp v7, v7, v7 row_ror:1 row_mask:0xf bank_mask:0xf bound_ctrl:1
	ds_bpermute_b32 v8, v5, v7
	s_waitcnt lgkmcnt(0)
	v_add_f32_e32 v7, v7, v8
	v_mov_b32_e32 v8, v7
	s_nop 1
	v_permlane32_swap_b32_e32 v7, v8
	v_add_f32_e32 v7, v7, v8
	v_mov_b32_e32 v8, 0x358637bd
	v_fmac_f32_e32 v8, 0x3a800000, v7
	v_rsq_f32_e32 v7, v8
	s_nop 0
	v_mul_f32_e32 v68, v68, v7
	v_mul_f32_e32 v69, v69, v7
	v_mul_f32_e32 v70, v70, v7
	v_mul_f32_e32 v71, v71, v7
	v_mul_f32_e32 v72, v72, v7
	v_mul_f32_e32 v73, v73, v7
	v_mul_f32_e32 v74, v74, v7
	v_mul_f32_e32 v75, v75, v7
	v_mul_f32_e32 v76, v76, v7
	v_mul_f32_e32 v77, v77, v7
	v_mul_f32_e32 v78, v78, v7
	v_mul_f32_e32 v79, v79, v7
	v_mul_f32_e32 v80, v80, v7
	v_mul_f32_e32 v81, v81, v7
	v_mul_f32_e32 v82, v82, v7
	v_mul_f32_e32 v83, v83, v7
	v_fma_f32 v68, v68, v20, v36
	v_fma_f32 v69, v69, v21, v37
	v_fma_f32 v70, v70, v22, v38
	v_fma_f32 v71, v71, v23, v39
	v_fma_f32 v72, v72, v24, v40
	v_fma_f32 v73, v73, v25, v41
	v_fma_f32 v74, v74, v26, v42
	v_fma_f32 v75, v75, v27, v43
	v_fma_f32 v76, v76, v28, v44
	v_fma_f32 v77, v77, v29, v45
	v_fma_f32 v78, v78, v30, v46
	v_fma_f32 v79, v79, v31, v47
	v_fma_f32 v80, v80, v32, v48
	v_fma_f32 v81, v81, v33, v49
	v_fma_f32 v82, v82, v34, v50
	v_fma_f32 v83, v83, v35, v51
	global_store_dwordx4 v2, v[68:71], s[26:27] offset:0
	global_store_dwordx4 v2, v[72:75], s[26:27] offset:1024
	global_store_dwordx4 v2, v[76:79], s[26:27] offset:2048
	global_store_dwordx4 v2, v[80:83], s[26:27] offset:3072
	s_cmp_lt_u32 s86, 3
	s_cbranch_scc0 .Llnl_nohB
; DI bf16 f2bf(float f) { unsigned u = __float_as_uint(f); u += 0x7fffu + ((u >> 16) & 1u); return (bf16)(u >> 16); }
;   DI float* MOD() const { return (float*)(p.ws + WS_MOD); }
;   DI bf16* HY() const { return (bf16*)(p.ws + WS_HY); }
; DI void ln_row(const Ctx& c, int row, int l_post, int l_next, int lane) {
;     ...
;     if (do_h) {
;       float s = 0.f;
; #pragma unroll
;       for (int i = 0; i < 16; ++i) s += v[i];
;       const float mean = wave_sum(s) * (1.f / D);
;       float q = 0.f;
; #pragma unroll
;       for (int i = 0; i < 16; ++i) { v[i] -= mean; q += v[i] * v[i]; }
;       const float rstd = rsqrtf(wave_sum(q) * (1.f / D) + LN_EPS);
;       const float* md = c.MOD() + (l_next * 3 + mod_row(row)) * 3072;
;       bf16* dst = c.HY() + (size_t)row * D;
; #pragma unroll
;       for (int i = 0; i < 4; ++i) {
;         const int col = i * 256 + lane * 4;
;         const float4 sh = *(const float4*)(md + col), sc = *(const float4*)(md + 1024 + col);
;         const float h0 = v[i * 4] * rstd * (1.f + sc.x) + sh.x, h1 = v[i * 4 + 1] * rstd * (1.f + sc.y) + sh.y;
;         const float h2 = v[i * 4 + 2] * rstd * (1.f + sc.z) + sh.z, h3 = v[i * 4 + 3] * rstd * (1.f + sc.w) + sh.w;
;         uint2 pk; pk.x = (unsigned)f2bf(h0) | ((unsigned)f2bf(h1) << 16); pk.y = (unsigned)f2bf(h2) | ((unsigned)f2bf(h3) << 16);
;         *(uint2*)(dst + col) = pk;
;       }
	s_lshr_b32 s26, s10, 1
	s_lshl_b32 s26, s26, 12
	s_and_b32 s2, s10, 1
	s_lshl_b32 s2, s2, 6
	s_or_b32 s26, s26, s2
	s_add_u32 s26, s88, s26
	s_addc_u32 s27, s89, 0
	s_add_u32 s26, s26, 0x1128000
	s_addc_u32 s27, s27, 0
	v_add_f32_e32 v6, v68, v69
	v_add_f32_e32 v6, v6, v70
	v_add_f32_e32 v6, v6, v71
	v_add_f32_e32 v6, v6, v72
	v_add_f32_e32 v6, v6, v73
	v_add_f32_e32 v6, v6, v74
	v_add_f32_e32 v6, v6, v75
	v_add_f32_e32 v6, v6, v76
	v_add_f32_e32 v6, v6, v77
	v_add_f32_e32 v6, v6, v78
	v_add_f32_e32 v6, v6, v79
	v_add_f32_e32 v6, v6, v80
	v_add_f32_e32 v6, v6, v81
	v_add_f32_e32 v6, v6, v82
	v_add_f32_e32 v6, v6, v83
	s_nop 1
	v_add_f32_dpp v6, v6, v6 row_ror:8 row_mask:0xf bank_mask:0xf bound_ctrl:1
	s_nop 1
	v_add_f32_dpp v6, v6, v6 row_ror:4 row_mask:0xf bank_mask:0xf bound_ctrl:1
	s_nop 1
	v_add_f32_dpp v6, v6, v6 row_ror:2 row_mask:0xf bank_mask:0xf bound_ctrl:1
	s_nop 1
	v_add_f32_dpp v6, v6, v6 row_ror:1 row_mask:0xf bank_mask:0xf bound_ctrl:1
	ds_bpermute_b32 v8, v5, v6
	s_waitcnt lgkmcnt(0)
	v_add_f32_e32 v6, v6, v8
	v_mov_b32_e32 v8, v6
	s_nop 1
	v_permlane32_swap_b32_e32 v6, v8
	v_add_f32_e32 v6, v6, v8
	v_mul_f32_e32 v6, 0x3a800000, v6
	v_sub_f32_e32 v68, v68, v6
	v_sub_f32_e32 v69, v69, v6
	v_sub_f32_e32 v70, v70, v6
	v_sub_f32_e32 v71, v71, v6
	v_sub_f32_e32 v72, v72, v6
	v_sub_f32_e32 v73, v73, v6
	v_sub_f32_e32 v74, v74, v6
	v_sub_f32_e32 v75, v75, v6
	v_sub_f32_e32 v76, v76, v6
	v_sub_f32_e32 v77, v77, v6
	v_sub_f32_e32 v78, v78, v6
	v_sub_f32_e32 v79, v79, v6
	v_sub_f32_e32 v80, v80, v6
	v_sub_f32_e32 v81, v81, v6
	v_sub_f32_e32 v82, v82, v6
	v_sub_f32_e32 v83, v83, v6
	v_mul_f32_e32 v7, v68, v68
	v_fmac_f32_e32 v7, v69, v69
	v_fmac_f32_e32 v7, v70, v70
	v_fmac_f32_e32 v7, v71, v71
	v_fmac_f32_e32 v7, v72, v72
	v_fmac_f32_e32 v7, v73, v73
	v_fmac_f32_e32 v7, v74, v74
	v_fmac_f32_e32 v7, v75, v75
	v_fmac_f32_e32 v7, v76, v76
	v_fmac_f32_e32 v7, v77, v77
	v_fmac_f32_e32 v7, v78, v78
	v_fmac_f32_e32 v7, v79, v79
	v_fmac_f32_e32 v7, v80, v80
	v_fmac_f32_e32 v7, v81, v81
	v_fmac_f32_e32 v7, v82, v82
	v_fmac_f32_e32 v7, v83, v83
	s_nop 1
	v_add_f32_dpp v7, v7, v7 row_ror:8 row_mask:0xf bank_mask:0xf bound_ctrl:1
	s_nop 1
	v_add_f32_dpp v7, v7, v7 row_ror:4 row_mask:0xf bank_mask:0xf bound_ctrl:1
	s_nop 1
	v_add_f32_dpp v7, v7, v7 row_ror:2 row_mask:0xf bank_mask:0xf bound_ctrl:1
	s_nop 1
	v_add_f32_dpp v7, v7, v7 row_ror:1 row_mask:0xf bank_mask:0xf bound_ctrl:1
	ds_bpermute_b32 v8, v5, v7
	s_waitcnt lgkmcnt(0)
	v_add_f32_e32 v7, v7, v8
	v_mov_b32_e32 v8, v7
	s_nop 1
	v_permlane32_swap_b32_e32 v7, v8
	v_add_f32_e32 v7, v7, v8
	v_mov_b32_e32 v8, 0x358637bd
	v_fmac_f32_e32 v8, 0x3a800000, v7
	v_rsq_f32_e32 v7, v8
	s_nop 0
	v_mul_f32_e32 v68, v68, v7
	v_mul_f32_e32 v69, v69, v7
	v_mul_f32_e32 v70, v70, v7
	v_mul_f32_e32 v71, v71, v7
	v_mul_f32_e32 v72, v72, v7
	v_mul_f32_e32 v73, v73, v7
	v_mul_f32_e32 v74, v74, v7
	v_mul_f32_e32 v75, v75, v7
	v_mul_f32_e32 v76, v76, v7
	v_mul_f32_e32 v77, v77, v7
	v_mul_f32_e32 v78, v78, v7
	v_mul_f32_e32 v79, v79, v7
	v_mul_f32_e32 v80, v80, v7
	v_mul_f32_e32 v81, v81, v7
	v_mul_f32_e32 v82, v82, v7
	v_mul_f32_e32 v83, v83, v7
	v_add_f32_e32 v132, 1.0, v132
	v_add_f32_e32 v133, 1.0, v133
	v_add_f32_e32 v134, 1.0, v134
	v_add_f32_e32 v135, 1.0, v135
	v_add_f32_e32 v136, 1.0, v136
	v_add_f32_e32 v137, 1.0, v137
	v_add_f32_e32 v138, 1.0, v138
	v_add_f32_e32 v139, 1.0, v139
	v_add_f32_e32 v140, 1.0, v140
	v_add_f32_e32 v141, 1.0, v141
	v_add_f32_e32 v142, 1.0, v142
	v_add_f32_e32 v143, 1.0, v143
	v_add_f32_e32 v144, 1.0, v144
	v_add_f32_e32 v145, 1.0, v145
	v_add_f32_e32 v146, 1.0, v146
	v_add_f32_e32 v147, 1.0, v147
	v_fma_f32 v68, v68, v132, v116
	v_fma_f32 v69, v69, v133, v117
	v_fma_f32 v70, v70, v134, v118
	v_fma_f32 v71, v71, v135, v119
	v_fma_f32 v72, v72, v136, v120
	v_fma_f32 v73, v73, v137, v121
	v_fma_f32 v74, v74, v138, v122
	v_fma_f32 v75, v75, v139, v123
	v_fma_f32 v76, v76, v140, v124
	v_fma_f32 v77, v77, v141, v125
	v_fma_f32 v78, v78, v142, v126
	v_fma_f32 v79, v79, v143, v127
	v_fma_f32 v80, v80, v144, v128
	v_fma_f32 v81, v81, v145, v129
	v_fma_f32 v82, v82, v146, v130
	v_fma_f32 v83, v83, v147, v131
	v_cvt_pk_bf16_f32 v68, v68, v69
	v_cvt_pk_bf16_f32 v69, v70, v71
	v_cvt_pk_bf16_f32 v70, v72, v73
	v_cvt_pk_bf16_f32 v71, v74, v75
	v_cvt_pk_bf16_f32 v72, v76, v77
	v_cvt_pk_bf16_f32 v73, v78, v79
	v_cvt_pk_bf16_f32 v74, v80, v81
	v_cvt_pk_bf16_f32 v75, v82, v83
	global_store_dwordx2 v14, v[68:69], s[26:27] offset:0
	global_store_dwordx2 v14, v[70:71], s[26:27] offset:1024
	global_store_dwordx2 v14, v[72:73], s[26:27] offset:2048
	global_store_dwordx2 v14, v[74:75], s[26:27] offset:3072
